# scan: scaled-state form (producer pre-divides by the running decay of each 8-step segment; consumer drops the per-step decay multiply and one LDS vector)
# speedup vs baseline: 1.0552x; 1.0148x over previous
.LBB0_1344:
	s_and_b32 s17, s61, 32
	s_mulk_i32 s17, 0x540
	s_add_i32 s56, s91, s17
	v_lshl_add_u32 v67, v77, 2, s56
	v_lshl_add_u32 v85, v60, 2, s56
	ds_read_b128 v[4:7], v67
	ds_read_b128 v[12:15], v67 offset:512
	ds_read_b128 v[8:11], v67 offset:256
	ds_read_b128 v[20:23], v67 offset:1024
	ds_read_b32 v74, v85 offset:1280
	ds_read_b128 v[24:27], v67 offset:1344
	ds_read_b128 v[32:35], v67 offset:1856
	ds_read_b128 v[28:31], v67 offset:1600
	ds_read_b128 v[40:43], v67 offset:2368
	ds_read_b32 v76, v85 offset:2624
	s_ashr_i32 s17, s16, 31
	s_lshl_b64 s[16:17], s[16:17], 11
	v_lshl_add_u64 v[72:73], v[68:69], 0, s[16:17]
	v_lshl_add_u64 v[72:73], v[70:71], 1, v[72:73]
	s_waitcnt lgkmcnt(5)
	v_pk_mul_f32 v[90:91], v[0:1], v[4:5]
	v_pk_fma_f32 v[86:87], v[12:13], v[74:75], v[0:1] op_sel_hi:[1,0,1]
	v_pk_fma_f32 v[90:91], v[2:3], v[6:7], v[90:91]
	ds_read_b128 v[44:47], v67 offset:2688
	v_pk_fma_f32 v[88:89], v[14:15], v[74:75], v[2:3] op_sel_hi:[1,0,1]
	v_add_f32_e32 v92, v90, v91
	ds_read_b128 v[52:55], v67 offset:3200
	ds_read_b128 v[48:51], v67 offset:2944
	v_add_f32_dpp v92, v92, v92 quad_perm:[1,0,3,2] row_mask:0xf bank_mask:0xf bound_ctrl:1
	ds_read_b128 v[80:83], v67 offset:3712
	ds_read_b32 v78, v85 offset:3968
	v_add_f32_dpp v92, v92, v92 quad_perm:[2,3,0,1] row_mask:0xf bank_mask:0xf bound_ctrl:1
	s_nop 1
	v_add_f32_dpp v92, v92, v92 row_half_mirror row_mask:0xf bank_mask:0xf bound_ctrl:1
	s_nop 1
	v_add_f32_dpp v92, v92, v92 row_mirror row_mask:0xf bank_mask:0xf bound_ctrl:1
	v_pk_fma_f32 v[0:1], v[8:9], v[92:93], v[86:87] op_sel_hi:[1,0,1]
	v_pk_fma_f32 v[2:3], v[10:11], v[92:93], v[88:89] op_sel_hi:[1,0,1]
	s_waitcnt lgkmcnt(5)
	v_pk_mul_f32 v[90:91], v[0:1], v[24:25]
	v_pk_fma_f32 v[86:87], v[32:33], v[76:77], v[0:1] op_sel_hi:[1,0,1]
	v_pk_fma_f32 v[90:91], v[2:3], v[26:27], v[90:91]
	v_pk_mul_f32 v[94:95], v[0:1], v[20:21]
	v_pk_fma_f32 v[88:89], v[34:35], v[76:77], v[2:3] op_sel_hi:[1,0,1]
	v_add_f32_e32 v92, v90, v91
	v_pk_fma_f32 v[94:95], v[2:3], v[22:23], v[94:95]
	ds_read_b128 v[4:7], v67 offset:4032
	v_add_f32_dpp v92, v92, v92 quad_perm:[1,0,3,2] row_mask:0xf bank_mask:0xf bound_ctrl:1
	ds_read_b128 v[12:15], v67 offset:4544
	ds_read_b128 v[8:11], v67 offset:4288
	v_add_f32_dpp v92, v92, v92 quad_perm:[2,3,0,1] row_mask:0xf bank_mask:0xf bound_ctrl:1
	ds_read_b128 v[20:23], v67 offset:5056
	ds_read_b32 v74, v85 offset:5312
	v_add_f32_dpp v92, v92, v92 row_half_mirror row_mask:0xf bank_mask:0xf bound_ctrl:1
	v_add_f32_e32 v96, v94, v95
	s_nop 0
	v_add_f32_dpp v92, v92, v92 row_mirror row_mask:0xf bank_mask:0xf bound_ctrl:1
	v_pk_fma_f32 v[0:1], v[28:29], v[92:93], v[86:87] op_sel_hi:[1,0,1]
	v_pk_fma_f32 v[2:3], v[30:31], v[92:93], v[88:89] op_sel_hi:[1,0,1]
	s_waitcnt lgkmcnt(5)
	v_pk_mul_f32 v[90:91], v[0:1], v[44:45]
	v_pk_fma_f32 v[86:87], v[52:53], v[78:79], v[0:1] op_sel_hi:[1,0,1]
	v_pk_fma_f32 v[90:91], v[2:3], v[46:47], v[90:91]
	v_pk_mul_f32 v[94:95], v[0:1], v[40:41]
	v_pk_fma_f32 v[88:89], v[54:55], v[78:79], v[2:3] op_sel_hi:[1,0,1]
	v_add_f32_e32 v92, v90, v91
	v_pk_fma_f32 v[94:95], v[2:3], v[42:43], v[94:95]
	ds_read_b128 v[24:27], v67 offset:5376
	v_add_f32_dpp v92, v92, v92 quad_perm:[1,0,3,2] row_mask:0xf bank_mask:0xf bound_ctrl:1
	ds_read_b128 v[32:35], v67 offset:5888
	ds_read_b128 v[28:31], v67 offset:5632
	v_add_f32_dpp v92, v92, v92 quad_perm:[2,3,0,1] row_mask:0xf bank_mask:0xf bound_ctrl:1
	ds_read_b128 v[40:43], v67 offset:6400
	ds_read_b32 v76, v85 offset:6656
	v_add_f32_dpp v92, v92, v92 row_half_mirror row_mask:0xf bank_mask:0xf bound_ctrl:1
	v_add_f32_e32 v97, v94, v95
	s_nop 0
	v_add_f32_dpp v92, v92, v92 row_mirror row_mask:0xf bank_mask:0xf bound_ctrl:1
	v_pk_fma_f32 v[0:1], v[48:49], v[92:93], v[86:87] op_sel_hi:[1,0,1]
	v_pk_fma_f32 v[2:3], v[50:51], v[92:93], v[88:89] op_sel_hi:[1,0,1]
	s_waitcnt lgkmcnt(5)
	v_pk_mul_f32 v[90:91], v[0:1], v[4:5]
	v_pk_fma_f32 v[86:87], v[12:13], v[74:75], v[0:1] op_sel_hi:[1,0,1]
	v_pk_fma_f32 v[90:91], v[2:3], v[6:7], v[90:91]
	v_pk_mul_f32 v[94:95], v[0:1], v[80:81]
	v_pk_fma_f32 v[88:89], v[14:15], v[74:75], v[2:3] op_sel_hi:[1,0,1]
	v_add_f32_e32 v92, v90, v91
	v_pk_fma_f32 v[94:95], v[2:3], v[82:83], v[94:95]
	ds_read_b128 v[44:47], v67 offset:6720
	v_add_f32_dpp v92, v92, v92 quad_perm:[1,0,3,2] row_mask:0xf bank_mask:0xf bound_ctrl:1
	ds_read_b128 v[52:55], v67 offset:7232
	ds_read_b128 v[48:51], v67 offset:6976
	v_add_f32_dpp v92, v92, v92 quad_perm:[2,3,0,1] row_mask:0xf bank_mask:0xf bound_ctrl:1
	ds_read_b128 v[80:83], v67 offset:7744
	ds_read_b32 v78, v85 offset:8000
	v_add_f32_dpp v92, v92, v92 row_half_mirror row_mask:0xf bank_mask:0xf bound_ctrl:1
	v_add_f32_e32 v98, v94, v95
	s_nop 0
	v_add_f32_dpp v92, v92, v92 row_mirror row_mask:0xf bank_mask:0xf bound_ctrl:1
	v_pk_fma_f32 v[0:1], v[8:9], v[92:93], v[86:87] op_sel_hi:[1,0,1]
	v_pk_fma_f32 v[2:3], v[10:11], v[92:93], v[88:89] op_sel_hi:[1,0,1]
	s_waitcnt lgkmcnt(5)
	v_pk_mul_f32 v[90:91], v[0:1], v[24:25]
	v_pk_fma_f32 v[86:87], v[32:33], v[76:77], v[0:1] op_sel_hi:[1,0,1]
	v_pk_fma_f32 v[90:91], v[2:3], v[26:27], v[90:91]
	v_pk_mul_f32 v[94:95], v[0:1], v[20:21]
	v_pk_fma_f32 v[88:89], v[34:35], v[76:77], v[2:3] op_sel_hi:[1,0,1]
	v_add_f32_e32 v92, v90, v91
	v_pk_fma_f32 v[94:95], v[2:3], v[22:23], v[94:95]
	ds_read_b128 v[4:7], v67 offset:8064
	v_add_f32_dpp v92, v92, v92 quad_perm:[1,0,3,2] row_mask:0xf bank_mask:0xf bound_ctrl:1
	ds_read_b128 v[12:15], v67 offset:8576
	ds_read_b128 v[8:11], v67 offset:8320
	v_add_f32_dpp v92, v92, v92 quad_perm:[2,3,0,1] row_mask:0xf bank_mask:0xf bound_ctrl:1
	ds_read_b128 v[20:23], v67 offset:9088
	ds_read_b32 v74, v85 offset:9344
	v_add_f32_dpp v92, v92, v92 row_half_mirror row_mask:0xf bank_mask:0xf bound_ctrl:1
	v_add_f32_e32 v99, v94, v95
	v_cndmask_b32_e64 v100, v98, v96, s[6:7]
	v_add_f32_dpp v92, v92, v92 row_mirror row_mask:0xf bank_mask:0xf bound_ctrl:1
	v_cndmask_b32_e64 v101, v96, v98, s[6:7]
	v_pk_fma_f32 v[0:1], v[28:29], v[92:93], v[86:87] op_sel_hi:[1,0,1]
	v_pk_fma_f32 v[2:3], v[30:31], v[92:93], v[88:89] op_sel_hi:[1,0,1]
	v_cndmask_b32_e64 v102, v99, v97, s[6:7]
	v_cndmask_b32_e64 v103, v97, v99, s[6:7]
	s_waitcnt lgkmcnt(5)
	v_pk_mul_f32 v[90:91], v[0:1], v[44:45]
	v_pk_fma_f32 v[86:87], v[52:53], v[78:79], v[0:1] op_sel_hi:[1,0,1]
	v_pk_fma_f32 v[90:91], v[2:3], v[46:47], v[90:91]
	v_pk_mul_f32 v[94:95], v[0:1], v[40:41]
	v_pk_fma_f32 v[88:89], v[54:55], v[78:79], v[2:3] op_sel_hi:[1,0,1]
	v_add_f32_e32 v92, v90, v91
	v_pk_fma_f32 v[94:95], v[2:3], v[42:43], v[94:95]
	ds_read_b128 v[24:27], v67 offset:9408
	v_add_f32_dpp v92, v92, v92 quad_perm:[1,0,3,2] row_mask:0xf bank_mask:0xf bound_ctrl:1
	ds_read_b128 v[32:35], v67 offset:9920
	ds_read_b128 v[28:31], v67 offset:9664
	v_add_f32_dpp v92, v92, v92 quad_perm:[2,3,0,1] row_mask:0xf bank_mask:0xf bound_ctrl:1
	ds_read_b128 v[40:43], v67 offset:10432
	ds_read_b32 v76, v85 offset:10688
	v_add_f32_dpp v92, v92, v92 row_half_mirror row_mask:0xf bank_mask:0xf bound_ctrl:1
	v_add_f32_e32 v96, v94, v95
	ds_read_b128 v[36:39], v67 offset:10176
	v_add_f32_dpp v92, v92, v92 row_mirror row_mask:0xf bank_mask:0xf bound_ctrl:1
	v_add_f32_dpp v100, v101, v100 quad_perm:[1,0,3,2] row_mask:0xf bank_mask:0xf bound_ctrl:1
	v_pk_fma_f32 v[0:1], v[48:49], v[92:93], v[86:87] op_sel_hi:[1,0,1]
	v_pk_fma_f32 v[2:3], v[50:51], v[92:93], v[88:89] op_sel_hi:[1,0,1]
	v_add_f32_dpp v103, v103, v102 quad_perm:[1,0,3,2] row_mask:0xf bank_mask:0xf bound_ctrl:1
	v_cndmask_b32_e64 v101, v103, v100, s[8:9]
	v_cndmask_b32_e64 v102, v100, v103, s[8:9]
	s_waitcnt lgkmcnt(6)
	v_pk_mul_f32 v[90:91], v[0:1], v[4:5]
	v_pk_fma_f32 v[86:87], v[12:13], v[74:75], v[0:1] op_sel_hi:[1,0,1]
	v_pk_fma_f32 v[90:91], v[2:3], v[6:7], v[90:91]
	v_pk_mul_f32 v[94:95], v[0:1], v[80:81]
	v_pk_fma_f32 v[88:89], v[14:15], v[74:75], v[2:3] op_sel_hi:[1,0,1]
	v_add_f32_e32 v92, v90, v91
	v_pk_fma_f32 v[94:95], v[2:3], v[82:83], v[94:95]
	ds_read_b128 v[44:47], v67 offset:10752
	v_add_f32_dpp v92, v92, v92 quad_perm:[1,0,3,2] row_mask:0xf bank_mask:0xf bound_ctrl:1
	ds_read_b128 v[52:55], v67 offset:11264
	ds_read_b128 v[48:51], v67 offset:11008
	v_add_f32_dpp v92, v92, v92 quad_perm:[2,3,0,1] row_mask:0xf bank_mask:0xf bound_ctrl:1
	ds_read_b128 v[80:83], v67 offset:11776
	ds_read_b32 v78, v85 offset:12032
	v_add_f32_dpp v92, v92, v92 row_half_mirror row_mask:0xf bank_mask:0xf bound_ctrl:1
	v_add_f32_e32 v97, v94, v95
	s_nop 0
	v_add_f32_dpp v92, v92, v92 row_mirror row_mask:0xf bank_mask:0xf bound_ctrl:1
	v_add_f32_dpp v102, v102, v101 quad_perm:[2,3,0,1] row_mask:0xf bank_mask:0xf bound_ctrl:1
	v_pk_fma_f32 v[0:1], v[8:9], v[92:93], v[86:87] op_sel_hi:[1,0,1]
	v_pk_fma_f32 v[2:3], v[10:11], v[92:93], v[88:89] op_sel_hi:[1,0,1]
	v_add_f32_dpp v102, v102, v102 row_ror:4 row_mask:0xf bank_mask:0xf bound_ctrl:1
	s_waitcnt lgkmcnt(5)
	v_pk_mul_f32 v[90:91], v[0:1], v[24:25]
	v_pk_fma_f32 v[86:87], v[32:33], v[76:77], v[0:1] op_sel_hi:[1,0,1]
	v_pk_fma_f32 v[90:91], v[2:3], v[26:27], v[90:91]
	v_pk_mul_f32 v[94:95], v[0:1], v[20:21]
	v_pk_fma_f32 v[88:89], v[34:35], v[76:77], v[2:3] op_sel_hi:[1,0,1]
	v_add_f32_e32 v92, v90, v91
	v_pk_fma_f32 v[94:95], v[2:3], v[22:23], v[94:95]
	ds_read_b128 v[4:7], v67 offset:12096
	v_add_f32_dpp v92, v92, v92 quad_perm:[1,0,3,2] row_mask:0xf bank_mask:0xf bound_ctrl:1
	ds_read_b128 v[12:15], v67 offset:12608
	ds_read_b128 v[8:11], v67 offset:12352
	v_add_f32_dpp v92, v92, v92 quad_perm:[2,3,0,1] row_mask:0xf bank_mask:0xf bound_ctrl:1
	ds_read_b128 v[20:23], v67 offset:13120
	ds_read_b32 v74, v85 offset:13376
	v_add_f32_dpp v92, v92, v92 row_half_mirror row_mask:0xf bank_mask:0xf bound_ctrl:1
	v_add_f32_e32 v98, v94, v95
	v_mov_b32_dpp v103, v102 row_ror:8 row_mask:0xf bank_mask:0xf bound_ctrl:1
	v_add_f32_dpp v92, v92, v92 row_mirror row_mask:0xf bank_mask:0xf bound_ctrl:1
	v_add_f32_e32 v100, v102, v103
	v_pk_fma_f32 v[0:1], v[28:29], v[92:93], v[86:87] op_sel_hi:[1,0,1]
	v_pk_fma_f32 v[2:3], v[30:31], v[92:93], v[88:89] op_sel_hi:[1,0,1]
	v_cvt_pk_bf16_f32 v100, v100, v100
	s_and_saveexec_b64 s[16:17], s[4:5]
	global_store_short v[72:73], v100, off
	s_or_b64 exec, exec, s[16:17]
	v_lshl_add_u64 v[72:73], v[72:73], 0, s[14:15]
	s_waitcnt lgkmcnt(5)
	v_pk_mul_f32 v[94:95], v[0:1], v[40:41]
	v_pk_fma_f32 v[94:95], v[2:3], v[42:43], v[94:95]
	v_pk_mul_f32 v[0:1], v[0:1], v[36:37]
	v_pk_mul_f32 v[2:3], v[2:3], v[38:39]
	ds_read_b128 v[24:27], v67 offset:13440
	v_pk_mul_f32 v[90:91], v[0:1], v[44:45]
	v_pk_fma_f32 v[86:87], v[52:53], v[78:79], v[0:1] op_sel_hi:[1,0,1]
	v_pk_fma_f32 v[90:91], v[2:3], v[46:47], v[90:91]
	ds_read_b128 v[32:35], v67 offset:13952
	v_pk_fma_f32 v[88:89], v[54:55], v[78:79], v[2:3] op_sel_hi:[1,0,1]
	v_add_f32_e32 v92, v90, v91
	ds_read_b128 v[28:31], v67 offset:13696
	ds_read_b128 v[40:43], v67 offset:14464
	v_add_f32_dpp v92, v92, v92 quad_perm:[1,0,3,2] row_mask:0xf bank_mask:0xf bound_ctrl:1
	ds_read_b32 v76, v85 offset:14720
	s_nop 0
	v_add_f32_dpp v92, v92, v92 quad_perm:[2,3,0,1] row_mask:0xf bank_mask:0xf bound_ctrl:1
	s_nop 1
	v_add_f32_dpp v92, v92, v92 row_half_mirror row_mask:0xf bank_mask:0xf bound_ctrl:1
	v_add_f32_e32 v99, v94, v95
	v_cndmask_b32_e64 v100, v98, v96, s[6:7]
	v_add_f32_dpp v92, v92, v92 row_mirror row_mask:0xf bank_mask:0xf bound_ctrl:1
	v_cndmask_b32_e64 v101, v96, v98, s[6:7]
	v_pk_fma_f32 v[0:1], v[48:49], v[92:93], v[86:87] op_sel_hi:[1,0,1]
	v_pk_fma_f32 v[2:3], v[50:51], v[92:93], v[88:89] op_sel_hi:[1,0,1]
	v_cndmask_b32_e64 v102, v99, v97, s[6:7]
	v_cndmask_b32_e64 v103, v97, v99, s[6:7]
	s_waitcnt lgkmcnt(5)
	v_pk_mul_f32 v[90:91], v[0:1], v[4:5]
	v_pk_fma_f32 v[86:87], v[12:13], v[74:75], v[0:1] op_sel_hi:[1,0,1]
	v_pk_fma_f32 v[90:91], v[2:3], v[6:7], v[90:91]
	v_pk_mul_f32 v[94:95], v[0:1], v[80:81]
	v_pk_fma_f32 v[88:89], v[14:15], v[74:75], v[2:3] op_sel_hi:[1,0,1]
	v_add_f32_e32 v92, v90, v91
	v_pk_fma_f32 v[94:95], v[2:3], v[82:83], v[94:95]
	ds_read_b128 v[44:47], v67 offset:14784
	v_add_f32_dpp v92, v92, v92 quad_perm:[1,0,3,2] row_mask:0xf bank_mask:0xf bound_ctrl:1
	ds_read_b128 v[52:55], v67 offset:15296
	ds_read_b128 v[48:51], v67 offset:15040
	v_add_f32_dpp v92, v92, v92 quad_perm:[2,3,0,1] row_mask:0xf bank_mask:0xf bound_ctrl:1
	ds_read_b128 v[80:83], v67 offset:15808
	ds_read_b32 v78, v85 offset:16064
	v_add_f32_dpp v92, v92, v92 row_half_mirror row_mask:0xf bank_mask:0xf bound_ctrl:1
	v_add_f32_e32 v96, v94, v95
	v_add_f32_dpp v100, v101, v100 quad_perm:[1,0,3,2] row_mask:0xf bank_mask:0xf bound_ctrl:1
	v_add_f32_dpp v92, v92, v92 row_mirror row_mask:0xf bank_mask:0xf bound_ctrl:1
	v_add_f32_dpp v103, v103, v102 quad_perm:[1,0,3,2] row_mask:0xf bank_mask:0xf bound_ctrl:1
	v_pk_fma_f32 v[0:1], v[8:9], v[92:93], v[86:87] op_sel_hi:[1,0,1]
	v_pk_fma_f32 v[2:3], v[10:11], v[92:93], v[88:89] op_sel_hi:[1,0,1]
	v_cndmask_b32_e64 v101, v103, v100, s[8:9]
	v_cndmask_b32_e64 v102, v100, v103, s[8:9]
	s_waitcnt lgkmcnt(5)
	v_pk_mul_f32 v[90:91], v[0:1], v[24:25]
	v_pk_fma_f32 v[86:87], v[32:33], v[76:77], v[0:1] op_sel_hi:[1,0,1]
	v_pk_fma_f32 v[90:91], v[2:3], v[26:27], v[90:91]
	v_pk_mul_f32 v[94:95], v[0:1], v[20:21]
	v_pk_fma_f32 v[88:89], v[34:35], v[76:77], v[2:3] op_sel_hi:[1,0,1]
	v_add_f32_e32 v92, v90, v91
	v_pk_fma_f32 v[94:95], v[2:3], v[22:23], v[94:95]
	ds_read_b128 v[4:7], v67 offset:16128
	v_add_f32_dpp v92, v92, v92 quad_perm:[1,0,3,2] row_mask:0xf bank_mask:0xf bound_ctrl:1
	ds_read_b128 v[12:15], v67 offset:16640
	ds_read_b128 v[8:11], v67 offset:16384
	v_add_f32_dpp v92, v92, v92 quad_perm:[2,3,0,1] row_mask:0xf bank_mask:0xf bound_ctrl:1
	ds_read_b128 v[20:23], v67 offset:17152
	ds_read_b32 v74, v85 offset:17408
	v_add_f32_dpp v92, v92, v92 row_half_mirror row_mask:0xf bank_mask:0xf bound_ctrl:1
	v_add_f32_e32 v97, v94, v95
	s_nop 0
	v_add_f32_dpp v92, v92, v92 row_mirror row_mask:0xf bank_mask:0xf bound_ctrl:1
	v_add_f32_dpp v102, v102, v101 quad_perm:[2,3,0,1] row_mask:0xf bank_mask:0xf bound_ctrl:1
	v_pk_fma_f32 v[0:1], v[28:29], v[92:93], v[86:87] op_sel_hi:[1,0,1]
	v_pk_fma_f32 v[2:3], v[30:31], v[92:93], v[88:89] op_sel_hi:[1,0,1]
	v_add_f32_dpp v102, v102, v102 row_ror:4 row_mask:0xf bank_mask:0xf bound_ctrl:1
	s_waitcnt lgkmcnt(5)
	v_pk_mul_f32 v[90:91], v[0:1], v[44:45]
	v_pk_fma_f32 v[86:87], v[52:53], v[78:79], v[0:1] op_sel_hi:[1,0,1]
	v_pk_fma_f32 v[90:91], v[2:3], v[46:47], v[90:91]
	v_pk_mul_f32 v[94:95], v[0:1], v[40:41]
	v_pk_fma_f32 v[88:89], v[54:55], v[78:79], v[2:3] op_sel_hi:[1,0,1]
	v_add_f32_e32 v92, v90, v91
	v_pk_fma_f32 v[94:95], v[2:3], v[42:43], v[94:95]
	ds_read_b128 v[24:27], v67 offset:17472
	v_add_f32_dpp v92, v92, v92 quad_perm:[1,0,3,2] row_mask:0xf bank_mask:0xf bound_ctrl:1
	ds_read_b128 v[32:35], v67 offset:17984
	ds_read_b128 v[28:31], v67 offset:17728
	v_add_f32_dpp v92, v92, v92 quad_perm:[2,3,0,1] row_mask:0xf bank_mask:0xf bound_ctrl:1
	ds_read_b128 v[40:43], v67 offset:18496
	ds_read_b32 v76, v85 offset:18752
	v_add_f32_dpp v92, v92, v92 row_half_mirror row_mask:0xf bank_mask:0xf bound_ctrl:1
	v_add_f32_e32 v98, v94, v95
	v_mov_b32_dpp v103, v102 row_ror:8 row_mask:0xf bank_mask:0xf bound_ctrl:1
	v_add_f32_dpp v92, v92, v92 row_mirror row_mask:0xf bank_mask:0xf bound_ctrl:1
	v_add_f32_e32 v100, v102, v103
	v_pk_fma_f32 v[0:1], v[48:49], v[92:93], v[86:87] op_sel_hi:[1,0,1]
	v_pk_fma_f32 v[2:3], v[50:51], v[92:93], v[88:89] op_sel_hi:[1,0,1]
	v_cvt_pk_bf16_f32 v100, v100, v100
	s_and_saveexec_b64 s[16:17], s[4:5]
	global_store_short v[72:73], v100, off
	s_or_b64 exec, exec, s[16:17]
	v_lshl_add_u64 v[72:73], v[72:73], 0, s[14:15]
	s_waitcnt lgkmcnt(5)
	v_pk_mul_f32 v[90:91], v[0:1], v[4:5]
	v_pk_fma_f32 v[86:87], v[12:13], v[74:75], v[0:1] op_sel_hi:[1,0,1]
	v_pk_fma_f32 v[90:91], v[2:3], v[6:7], v[90:91]
	v_pk_mul_f32 v[94:95], v[0:1], v[80:81]
	v_pk_fma_f32 v[88:89], v[14:15], v[74:75], v[2:3] op_sel_hi:[1,0,1]
	v_add_f32_e32 v92, v90, v91
	v_pk_fma_f32 v[94:95], v[2:3], v[82:83], v[94:95]
	ds_read_b128 v[44:47], v67 offset:18816
	v_add_f32_dpp v92, v92, v92 quad_perm:[1,0,3,2] row_mask:0xf bank_mask:0xf bound_ctrl:1
	ds_read_b128 v[52:55], v67 offset:19328
	ds_read_b128 v[48:51], v67 offset:19072
	v_add_f32_dpp v92, v92, v92 quad_perm:[2,3,0,1] row_mask:0xf bank_mask:0xf bound_ctrl:1
	ds_read_b128 v[80:83], v67 offset:19840
	ds_read_b32 v78, v85 offset:20096
	v_add_f32_dpp v92, v92, v92 row_half_mirror row_mask:0xf bank_mask:0xf bound_ctrl:1
	v_add_f32_e32 v99, v94, v95
	v_cndmask_b32_e64 v100, v98, v96, s[6:7]
	v_add_f32_dpp v92, v92, v92 row_mirror row_mask:0xf bank_mask:0xf bound_ctrl:1
	v_cndmask_b32_e64 v101, v96, v98, s[6:7]
	v_pk_fma_f32 v[0:1], v[8:9], v[92:93], v[86:87] op_sel_hi:[1,0,1]
	v_pk_fma_f32 v[2:3], v[10:11], v[92:93], v[88:89] op_sel_hi:[1,0,1]
	v_cndmask_b32_e64 v102, v99, v97, s[6:7]
	v_cndmask_b32_e64 v103, v97, v99, s[6:7]
	s_waitcnt lgkmcnt(5)
	v_pk_mul_f32 v[90:91], v[0:1], v[24:25]
	v_pk_fma_f32 v[86:87], v[32:33], v[76:77], v[0:1] op_sel_hi:[1,0,1]
	v_pk_fma_f32 v[90:91], v[2:3], v[26:27], v[90:91]
	v_pk_mul_f32 v[94:95], v[0:1], v[20:21]
	v_pk_fma_f32 v[88:89], v[34:35], v[76:77], v[2:3] op_sel_hi:[1,0,1]
	v_add_f32_e32 v92, v90, v91
	v_pk_fma_f32 v[94:95], v[2:3], v[22:23], v[94:95]
	ds_read_b128 v[4:7], v67 offset:20160
	v_add_f32_dpp v92, v92, v92 quad_perm:[1,0,3,2] row_mask:0xf bank_mask:0xf bound_ctrl:1
	ds_read_b128 v[12:15], v67 offset:20672
	ds_read_b128 v[8:11], v67 offset:20416
	v_add_f32_dpp v92, v92, v92 quad_perm:[2,3,0,1] row_mask:0xf bank_mask:0xf bound_ctrl:1
	ds_read_b128 v[20:23], v67 offset:21184
	ds_read_b32 v74, v85 offset:21440
	v_add_f32_dpp v92, v92, v92 row_half_mirror row_mask:0xf bank_mask:0xf bound_ctrl:1
	v_add_f32_e32 v96, v94, v95
	ds_read_b128 v[16:19], v67 offset:20928
	v_add_f32_dpp v92, v92, v92 row_mirror row_mask:0xf bank_mask:0xf bound_ctrl:1
	v_add_f32_dpp v100, v101, v100 quad_perm:[1,0,3,2] row_mask:0xf bank_mask:0xf bound_ctrl:1
	v_pk_fma_f32 v[0:1], v[28:29], v[92:93], v[86:87] op_sel_hi:[1,0,1]
	v_pk_fma_f32 v[2:3], v[30:31], v[92:93], v[88:89] op_sel_hi:[1,0,1]
	v_add_f32_dpp v103, v103, v102 quad_perm:[1,0,3,2] row_mask:0xf bank_mask:0xf bound_ctrl:1
	v_cndmask_b32_e64 v101, v103, v100, s[8:9]
	v_cndmask_b32_e64 v102, v100, v103, s[8:9]
	s_waitcnt lgkmcnt(6)
	v_pk_mul_f32 v[90:91], v[0:1], v[44:45]
	v_pk_fma_f32 v[86:87], v[52:53], v[78:79], v[0:1] op_sel_hi:[1,0,1]
	v_pk_fma_f32 v[90:91], v[2:3], v[46:47], v[90:91]
	v_pk_mul_f32 v[94:95], v[0:1], v[40:41]
	v_pk_fma_f32 v[88:89], v[54:55], v[78:79], v[2:3] op_sel_hi:[1,0,1]
	v_add_f32_e32 v92, v90, v91
	v_pk_fma_f32 v[94:95], v[2:3], v[42:43], v[94:95]
	ds_read_b128 v[24:27], v67 offset:21504
	v_add_f32_dpp v92, v92, v92 quad_perm:[1,0,3,2] row_mask:0xf bank_mask:0xf bound_ctrl:1
	ds_read_b128 v[32:35], v67 offset:22016
	ds_read_b128 v[28:31], v67 offset:21760
	v_add_f32_dpp v92, v92, v92 quad_perm:[2,3,0,1] row_mask:0xf bank_mask:0xf bound_ctrl:1
	ds_read_b128 v[40:43], v67 offset:22528
	ds_read_b32 v76, v85 offset:22784
	v_add_f32_dpp v92, v92, v92 row_half_mirror row_mask:0xf bank_mask:0xf bound_ctrl:1
	v_add_f32_e32 v97, v94, v95
	s_nop 0
	v_add_f32_dpp v92, v92, v92 row_mirror row_mask:0xf bank_mask:0xf bound_ctrl:1
	v_add_f32_dpp v102, v102, v101 quad_perm:[2,3,0,1] row_mask:0xf bank_mask:0xf bound_ctrl:1
	v_pk_fma_f32 v[0:1], v[48:49], v[92:93], v[86:87] op_sel_hi:[1,0,1]
	v_pk_fma_f32 v[2:3], v[50:51], v[92:93], v[88:89] op_sel_hi:[1,0,1]
	v_add_f32_dpp v102, v102, v102 row_ror:4 row_mask:0xf bank_mask:0xf bound_ctrl:1
	s_waitcnt lgkmcnt(5)
	v_pk_mul_f32 v[90:91], v[0:1], v[4:5]
	v_pk_fma_f32 v[86:87], v[12:13], v[74:75], v[0:1] op_sel_hi:[1,0,1]
	v_pk_fma_f32 v[90:91], v[2:3], v[6:7], v[90:91]
	v_pk_mul_f32 v[94:95], v[0:1], v[80:81]
	v_pk_fma_f32 v[88:89], v[14:15], v[74:75], v[2:3] op_sel_hi:[1,0,1]
	v_add_f32_e32 v92, v90, v91
	v_pk_fma_f32 v[94:95], v[2:3], v[82:83], v[94:95]
	ds_read_b128 v[44:47], v67 offset:22848
	v_add_f32_dpp v92, v92, v92 quad_perm:[1,0,3,2] row_mask:0xf bank_mask:0xf bound_ctrl:1
	ds_read_b128 v[52:55], v67 offset:23360
	ds_read_b128 v[48:51], v67 offset:23104
	v_add_f32_dpp v92, v92, v92 quad_perm:[2,3,0,1] row_mask:0xf bank_mask:0xf bound_ctrl:1
	ds_read_b128 v[80:83], v67 offset:23872
	ds_read_b32 v78, v85 offset:24128
	v_add_f32_dpp v92, v92, v92 row_half_mirror row_mask:0xf bank_mask:0xf bound_ctrl:1
	v_add_f32_e32 v98, v94, v95
	v_mov_b32_dpp v103, v102 row_ror:8 row_mask:0xf bank_mask:0xf bound_ctrl:1
	v_add_f32_dpp v92, v92, v92 row_mirror row_mask:0xf bank_mask:0xf bound_ctrl:1
	v_add_f32_e32 v100, v102, v103
	v_pk_fma_f32 v[0:1], v[8:9], v[92:93], v[86:87] op_sel_hi:[1,0,1]
	v_pk_fma_f32 v[2:3], v[10:11], v[92:93], v[88:89] op_sel_hi:[1,0,1]
	v_cvt_pk_bf16_f32 v100, v100, v100
	s_and_saveexec_b64 s[16:17], s[4:5]
	global_store_short v[72:73], v100, off
	s_or_b64 exec, exec, s[16:17]
	v_lshl_add_u64 v[72:73], v[72:73], 0, s[14:15]
	s_waitcnt lgkmcnt(5)
	v_pk_mul_f32 v[94:95], v[0:1], v[20:21]
	v_pk_fma_f32 v[94:95], v[2:3], v[22:23], v[94:95]
	v_pk_mul_f32 v[0:1], v[0:1], v[16:17]
	v_pk_mul_f32 v[2:3], v[2:3], v[18:19]
	ds_read_b128 v[4:7], v67 offset:24192
	v_pk_mul_f32 v[90:91], v[0:1], v[24:25]
	v_pk_fma_f32 v[86:87], v[32:33], v[76:77], v[0:1] op_sel_hi:[1,0,1]
	v_pk_fma_f32 v[90:91], v[2:3], v[26:27], v[90:91]
	ds_read_b128 v[12:15], v67 offset:24704
	v_pk_fma_f32 v[88:89], v[34:35], v[76:77], v[2:3] op_sel_hi:[1,0,1]
	v_add_f32_e32 v92, v90, v91
	ds_read_b128 v[8:11], v67 offset:24448
	ds_read_b128 v[20:23], v67 offset:25216
	v_add_f32_dpp v92, v92, v92 quad_perm:[1,0,3,2] row_mask:0xf bank_mask:0xf bound_ctrl:1
	ds_read_b32 v74, v85 offset:25472
	s_nop 0
	v_add_f32_dpp v92, v92, v92 quad_perm:[2,3,0,1] row_mask:0xf bank_mask:0xf bound_ctrl:1
	s_nop 1
	v_add_f32_dpp v92, v92, v92 row_half_mirror row_mask:0xf bank_mask:0xf bound_ctrl:1
	v_add_f32_e32 v99, v94, v95
	v_cndmask_b32_e64 v100, v98, v96, s[6:7]
	v_add_f32_dpp v92, v92, v92 row_mirror row_mask:0xf bank_mask:0xf bound_ctrl:1
	v_cndmask_b32_e64 v101, v96, v98, s[6:7]
	v_pk_fma_f32 v[0:1], v[28:29], v[92:93], v[86:87] op_sel_hi:[1,0,1]
	v_pk_fma_f32 v[2:3], v[30:31], v[92:93], v[88:89] op_sel_hi:[1,0,1]
	v_cndmask_b32_e64 v102, v99, v97, s[6:7]
	v_cndmask_b32_e64 v103, v97, v99, s[6:7]
	s_waitcnt lgkmcnt(5)
	v_pk_mul_f32 v[90:91], v[0:1], v[44:45]
	v_pk_fma_f32 v[86:87], v[52:53], v[78:79], v[0:1] op_sel_hi:[1,0,1]
	v_pk_fma_f32 v[90:91], v[2:3], v[46:47], v[90:91]
	v_pk_mul_f32 v[94:95], v[0:1], v[40:41]
	v_pk_fma_f32 v[88:89], v[54:55], v[78:79], v[2:3] op_sel_hi:[1,0,1]
	v_add_f32_e32 v92, v90, v91
	v_pk_fma_f32 v[94:95], v[2:3], v[42:43], v[94:95]
	ds_read_b128 v[24:27], v67 offset:25536
	v_add_f32_dpp v92, v92, v92 quad_perm:[1,0,3,2] row_mask:0xf bank_mask:0xf bound_ctrl:1
	ds_read_b128 v[32:35], v67 offset:26048
	ds_read_b128 v[28:31], v67 offset:25792
	v_add_f32_dpp v92, v92, v92 quad_perm:[2,3,0,1] row_mask:0xf bank_mask:0xf bound_ctrl:1
	ds_read_b128 v[40:43], v67 offset:26560
	ds_read_b32 v76, v85 offset:26816
	v_add_f32_dpp v92, v92, v92 row_half_mirror row_mask:0xf bank_mask:0xf bound_ctrl:1
	v_add_f32_e32 v96, v94, v95
	v_add_f32_dpp v100, v101, v100 quad_perm:[1,0,3,2] row_mask:0xf bank_mask:0xf bound_ctrl:1
	v_add_f32_dpp v92, v92, v92 row_mirror row_mask:0xf bank_mask:0xf bound_ctrl:1
	v_add_f32_dpp v103, v103, v102 quad_perm:[1,0,3,2] row_mask:0xf bank_mask:0xf bound_ctrl:1
	v_pk_fma_f32 v[0:1], v[48:49], v[92:93], v[86:87] op_sel_hi:[1,0,1]
	v_pk_fma_f32 v[2:3], v[50:51], v[92:93], v[88:89] op_sel_hi:[1,0,1]
	v_cndmask_b32_e64 v101, v103, v100, s[8:9]
	v_cndmask_b32_e64 v102, v100, v103, s[8:9]
	s_waitcnt lgkmcnt(5)
	v_pk_mul_f32 v[90:91], v[0:1], v[4:5]
	v_pk_fma_f32 v[86:87], v[12:13], v[74:75], v[0:1] op_sel_hi:[1,0,1]
	v_pk_fma_f32 v[90:91], v[2:3], v[6:7], v[90:91]
	v_pk_mul_f32 v[94:95], v[0:1], v[80:81]
	v_pk_fma_f32 v[88:89], v[14:15], v[74:75], v[2:3] op_sel_hi:[1,0,1]
	v_add_f32_e32 v92, v90, v91
	v_pk_fma_f32 v[94:95], v[2:3], v[82:83], v[94:95]
	ds_read_b128 v[44:47], v67 offset:26880
	v_add_f32_dpp v92, v92, v92 quad_perm:[1,0,3,2] row_mask:0xf bank_mask:0xf bound_ctrl:1
	ds_read_b128 v[52:55], v67 offset:27392
	ds_read_b128 v[48:51], v67 offset:27136
	v_add_f32_dpp v92, v92, v92 quad_perm:[2,3,0,1] row_mask:0xf bank_mask:0xf bound_ctrl:1
	ds_read_b128 v[80:83], v67 offset:27904
	ds_read_b32 v78, v85 offset:28160
	v_add_f32_dpp v92, v92, v92 row_half_mirror row_mask:0xf bank_mask:0xf bound_ctrl:1
	v_add_f32_e32 v97, v94, v95
	s_nop 0
	v_add_f32_dpp v92, v92, v92 row_mirror row_mask:0xf bank_mask:0xf bound_ctrl:1
	v_add_f32_dpp v102, v102, v101 quad_perm:[2,3,0,1] row_mask:0xf bank_mask:0xf bound_ctrl:1
	v_pk_fma_f32 v[0:1], v[8:9], v[92:93], v[86:87] op_sel_hi:[1,0,1]
	v_pk_fma_f32 v[2:3], v[10:11], v[92:93], v[88:89] op_sel_hi:[1,0,1]
	v_add_f32_dpp v102, v102, v102 row_ror:4 row_mask:0xf bank_mask:0xf bound_ctrl:1
	s_waitcnt lgkmcnt(5)
	v_pk_mul_f32 v[90:91], v[0:1], v[24:25]
	v_pk_fma_f32 v[86:87], v[32:33], v[76:77], v[0:1] op_sel_hi:[1,0,1]
	v_pk_fma_f32 v[90:91], v[2:3], v[26:27], v[90:91]
	v_pk_mul_f32 v[94:95], v[0:1], v[20:21]
	v_pk_fma_f32 v[88:89], v[34:35], v[76:77], v[2:3] op_sel_hi:[1,0,1]
	v_add_f32_e32 v92, v90, v91
	v_pk_fma_f32 v[94:95], v[2:3], v[22:23], v[94:95]
	ds_read_b128 v[4:7], v67 offset:28224
	v_add_f32_dpp v92, v92, v92 quad_perm:[1,0,3,2] row_mask:0xf bank_mask:0xf bound_ctrl:1
	ds_read_b128 v[12:15], v67 offset:28736
	ds_read_b128 v[8:11], v67 offset:28480
	v_add_f32_dpp v92, v92, v92 quad_perm:[2,3,0,1] row_mask:0xf bank_mask:0xf bound_ctrl:1
	ds_read_b128 v[20:23], v67 offset:29248
	ds_read_b32 v74, v85 offset:29504
	v_add_f32_dpp v92, v92, v92 row_half_mirror row_mask:0xf bank_mask:0xf bound_ctrl:1
	v_add_f32_e32 v98, v94, v95
	v_mov_b32_dpp v103, v102 row_ror:8 row_mask:0xf bank_mask:0xf bound_ctrl:1
	v_add_f32_dpp v92, v92, v92 row_mirror row_mask:0xf bank_mask:0xf bound_ctrl:1
	v_add_f32_e32 v100, v102, v103
	v_pk_fma_f32 v[0:1], v[28:29], v[92:93], v[86:87] op_sel_hi:[1,0,1]
	v_pk_fma_f32 v[2:3], v[30:31], v[92:93], v[88:89] op_sel_hi:[1,0,1]
	v_cvt_pk_bf16_f32 v100, v100, v100
	s_and_saveexec_b64 s[16:17], s[4:5]
	global_store_short v[72:73], v100, off
	s_or_b64 exec, exec, s[16:17]
	v_lshl_add_u64 v[72:73], v[72:73], 0, s[14:15]
	s_waitcnt lgkmcnt(5)
	v_pk_mul_f32 v[90:91], v[0:1], v[44:45]
	v_pk_fma_f32 v[86:87], v[52:53], v[78:79], v[0:1] op_sel_hi:[1,0,1]
	v_pk_fma_f32 v[90:91], v[2:3], v[46:47], v[90:91]
	v_pk_mul_f32 v[94:95], v[0:1], v[40:41]
	v_pk_fma_f32 v[88:89], v[54:55], v[78:79], v[2:3] op_sel_hi:[1,0,1]
	v_add_f32_e32 v92, v90, v91
	v_pk_fma_f32 v[94:95], v[2:3], v[42:43], v[94:95]
	ds_read_b128 v[24:27], v67 offset:29568
	v_add_f32_dpp v92, v92, v92 quad_perm:[1,0,3,2] row_mask:0xf bank_mask:0xf bound_ctrl:1
	ds_read_b128 v[32:35], v67 offset:30080
	ds_read_b128 v[28:31], v67 offset:29824
	v_add_f32_dpp v92, v92, v92 quad_perm:[2,3,0,1] row_mask:0xf bank_mask:0xf bound_ctrl:1
	ds_read_b128 v[40:43], v67 offset:30592
	ds_read_b32 v76, v85 offset:30848
	v_add_f32_dpp v92, v92, v92 row_half_mirror row_mask:0xf bank_mask:0xf bound_ctrl:1
	v_add_f32_e32 v99, v94, v95
	v_cndmask_b32_e64 v100, v98, v96, s[6:7]
	v_add_f32_dpp v92, v92, v92 row_mirror row_mask:0xf bank_mask:0xf bound_ctrl:1
	v_cndmask_b32_e64 v101, v96, v98, s[6:7]
	v_pk_fma_f32 v[0:1], v[48:49], v[92:93], v[86:87] op_sel_hi:[1,0,1]
	v_pk_fma_f32 v[2:3], v[50:51], v[92:93], v[88:89] op_sel_hi:[1,0,1]
	v_cndmask_b32_e64 v102, v99, v97, s[6:7]
	v_cndmask_b32_e64 v103, v97, v99, s[6:7]
	s_waitcnt lgkmcnt(5)
	v_pk_mul_f32 v[90:91], v[0:1], v[4:5]
	v_pk_fma_f32 v[86:87], v[12:13], v[74:75], v[0:1] op_sel_hi:[1,0,1]
	v_pk_fma_f32 v[90:91], v[2:3], v[6:7], v[90:91]
	v_pk_mul_f32 v[94:95], v[0:1], v[80:81]
	v_pk_fma_f32 v[88:89], v[14:15], v[74:75], v[2:3] op_sel_hi:[1,0,1]
	v_add_f32_e32 v92, v90, v91
	v_pk_fma_f32 v[94:95], v[2:3], v[82:83], v[94:95]
	ds_read_b128 v[44:47], v67 offset:30912
	v_add_f32_dpp v92, v92, v92 quad_perm:[1,0,3,2] row_mask:0xf bank_mask:0xf bound_ctrl:1
	ds_read_b128 v[52:55], v67 offset:31424
	ds_read_b128 v[48:51], v67 offset:31168
	v_add_f32_dpp v92, v92, v92 quad_perm:[2,3,0,1] row_mask:0xf bank_mask:0xf bound_ctrl:1
	ds_read_b128 v[80:83], v67 offset:31936
	ds_read_b32 v78, v85 offset:32192
	v_add_f32_dpp v92, v92, v92 row_half_mirror row_mask:0xf bank_mask:0xf bound_ctrl:1
	v_add_f32_e32 v96, v94, v95
	ds_read_b128 v[56:59], v67 offset:31680
	v_add_f32_dpp v92, v92, v92 row_mirror row_mask:0xf bank_mask:0xf bound_ctrl:1
	v_add_f32_dpp v100, v101, v100 quad_perm:[1,0,3,2] row_mask:0xf bank_mask:0xf bound_ctrl:1
	v_pk_fma_f32 v[0:1], v[8:9], v[92:93], v[86:87] op_sel_hi:[1,0,1]
	v_pk_fma_f32 v[2:3], v[10:11], v[92:93], v[88:89] op_sel_hi:[1,0,1]
	v_add_f32_dpp v103, v103, v102 quad_perm:[1,0,3,2] row_mask:0xf bank_mask:0xf bound_ctrl:1
	v_cndmask_b32_e64 v101, v103, v100, s[8:9]
	v_cndmask_b32_e64 v102, v100, v103, s[8:9]
	s_waitcnt lgkmcnt(6)
	v_pk_mul_f32 v[90:91], v[0:1], v[24:25]
	v_pk_fma_f32 v[86:87], v[32:33], v[76:77], v[0:1] op_sel_hi:[1,0,1]
	v_pk_fma_f32 v[90:91], v[2:3], v[26:27], v[90:91]
	v_pk_mul_f32 v[94:95], v[0:1], v[20:21]
	v_pk_fma_f32 v[88:89], v[34:35], v[76:77], v[2:3] op_sel_hi:[1,0,1]
	v_add_f32_e32 v92, v90, v91
	v_pk_fma_f32 v[94:95], v[2:3], v[22:23], v[94:95]
	ds_read_b128 v[4:7], v67 offset:32256
	v_add_f32_dpp v92, v92, v92 quad_perm:[1,0,3,2] row_mask:0xf bank_mask:0xf bound_ctrl:1
	ds_read_b128 v[12:15], v67 offset:32768
	ds_read_b128 v[8:11], v67 offset:32512
	v_add_f32_dpp v92, v92, v92 quad_perm:[2,3,0,1] row_mask:0xf bank_mask:0xf bound_ctrl:1
	ds_read_b128 v[20:23], v67 offset:33280
	ds_read_b32 v74, v85 offset:33536
	v_add_f32_dpp v92, v92, v92 row_half_mirror row_mask:0xf bank_mask:0xf bound_ctrl:1
	v_add_f32_e32 v97, v94, v95
	s_nop 0
	v_add_f32_dpp v92, v92, v92 row_mirror row_mask:0xf bank_mask:0xf bound_ctrl:1
	v_add_f32_dpp v102, v102, v101 quad_perm:[2,3,0,1] row_mask:0xf bank_mask:0xf bound_ctrl:1
	v_pk_fma_f32 v[0:1], v[28:29], v[92:93], v[86:87] op_sel_hi:[1,0,1]
	v_pk_fma_f32 v[2:3], v[30:31], v[92:93], v[88:89] op_sel_hi:[1,0,1]
	v_add_f32_dpp v102, v102, v102 row_ror:4 row_mask:0xf bank_mask:0xf bound_ctrl:1
	s_waitcnt lgkmcnt(5)
	v_pk_mul_f32 v[90:91], v[0:1], v[44:45]
	v_pk_fma_f32 v[86:87], v[52:53], v[78:79], v[0:1] op_sel_hi:[1,0,1]
	v_pk_fma_f32 v[90:91], v[2:3], v[46:47], v[90:91]
	v_pk_mul_f32 v[94:95], v[0:1], v[40:41]
	v_pk_fma_f32 v[88:89], v[54:55], v[78:79], v[2:3] op_sel_hi:[1,0,1]
	v_add_f32_e32 v92, v90, v91
	v_pk_fma_f32 v[94:95], v[2:3], v[42:43], v[94:95]
	ds_read_b128 v[24:27], v67 offset:33600
	v_add_f32_dpp v92, v92, v92 quad_perm:[1,0,3,2] row_mask:0xf bank_mask:0xf bound_ctrl:1
	ds_read_b128 v[32:35], v67 offset:34112
	ds_read_b128 v[28:31], v67 offset:33856
	v_add_f32_dpp v92, v92, v92 quad_perm:[2,3,0,1] row_mask:0xf bank_mask:0xf bound_ctrl:1
	ds_read_b128 v[40:43], v67 offset:34624
	ds_read_b32 v76, v85 offset:34880
	v_add_f32_dpp v92, v92, v92 row_half_mirror row_mask:0xf bank_mask:0xf bound_ctrl:1
	v_add_f32_e32 v98, v94, v95
	v_mov_b32_dpp v103, v102 row_ror:8 row_mask:0xf bank_mask:0xf bound_ctrl:1
	v_add_f32_dpp v92, v92, v92 row_mirror row_mask:0xf bank_mask:0xf bound_ctrl:1
	v_add_f32_e32 v100, v102, v103
	v_pk_fma_f32 v[0:1], v[48:49], v[92:93], v[86:87] op_sel_hi:[1,0,1]
	v_pk_fma_f32 v[2:3], v[50:51], v[92:93], v[88:89] op_sel_hi:[1,0,1]
	v_cvt_pk_bf16_f32 v100, v100, v100
	s_and_saveexec_b64 s[16:17], s[4:5]
	global_store_short v[72:73], v100, off
	s_or_b64 exec, exec, s[16:17]
	v_lshl_add_u64 v[72:73], v[72:73], 0, s[14:15]
	s_waitcnt lgkmcnt(5)
	v_pk_mul_f32 v[94:95], v[0:1], v[80:81]
	v_pk_fma_f32 v[94:95], v[2:3], v[82:83], v[94:95]
	v_pk_mul_f32 v[0:1], v[0:1], v[56:57]
	v_pk_mul_f32 v[2:3], v[2:3], v[58:59]
	ds_read_b128 v[44:47], v67 offset:34944
	v_pk_mul_f32 v[90:91], v[0:1], v[4:5]
	v_pk_fma_f32 v[86:87], v[12:13], v[74:75], v[0:1] op_sel_hi:[1,0,1]
	v_pk_fma_f32 v[90:91], v[2:3], v[6:7], v[90:91]
	ds_read_b128 v[52:55], v67 offset:35456
	v_pk_fma_f32 v[88:89], v[14:15], v[74:75], v[2:3] op_sel_hi:[1,0,1]
	v_add_f32_e32 v92, v90, v91
	ds_read_b128 v[48:51], v67 offset:35200
	ds_read_b128 v[80:83], v67 offset:35968
	v_add_f32_dpp v92, v92, v92 quad_perm:[1,0,3,2] row_mask:0xf bank_mask:0xf bound_ctrl:1
	ds_read_b32 v78, v85 offset:36224
	s_nop 0
	v_add_f32_dpp v92, v92, v92 quad_perm:[2,3,0,1] row_mask:0xf bank_mask:0xf bound_ctrl:1
	s_nop 1
	v_add_f32_dpp v92, v92, v92 row_half_mirror row_mask:0xf bank_mask:0xf bound_ctrl:1
	v_add_f32_e32 v99, v94, v95
	v_cndmask_b32_e64 v100, v98, v96, s[6:7]
	v_add_f32_dpp v92, v92, v92 row_mirror row_mask:0xf bank_mask:0xf bound_ctrl:1
	v_cndmask_b32_e64 v101, v96, v98, s[6:7]
	v_pk_fma_f32 v[0:1], v[8:9], v[92:93], v[86:87] op_sel_hi:[1,0,1]
	v_pk_fma_f32 v[2:3], v[10:11], v[92:93], v[88:89] op_sel_hi:[1,0,1]
	v_cndmask_b32_e64 v102, v99, v97, s[6:7]
	v_cndmask_b32_e64 v103, v97, v99, s[6:7]
	s_waitcnt lgkmcnt(5)
	v_pk_mul_f32 v[90:91], v[0:1], v[24:25]
	v_pk_fma_f32 v[86:87], v[32:33], v[76:77], v[0:1] op_sel_hi:[1,0,1]
	v_pk_fma_f32 v[90:91], v[2:3], v[26:27], v[90:91]
	v_pk_mul_f32 v[94:95], v[0:1], v[20:21]
	v_pk_fma_f32 v[88:89], v[34:35], v[76:77], v[2:3] op_sel_hi:[1,0,1]
	v_add_f32_e32 v92, v90, v91
	v_pk_fma_f32 v[94:95], v[2:3], v[22:23], v[94:95]
	ds_read_b128 v[4:7], v67 offset:36288
	v_add_f32_dpp v92, v92, v92 quad_perm:[1,0,3,2] row_mask:0xf bank_mask:0xf bound_ctrl:1
	ds_read_b128 v[12:15], v67 offset:36800
	ds_read_b128 v[8:11], v67 offset:36544
	v_add_f32_dpp v92, v92, v92 quad_perm:[2,3,0,1] row_mask:0xf bank_mask:0xf bound_ctrl:1
	ds_read_b128 v[20:23], v67 offset:37312
	ds_read_b32 v74, v85 offset:37568
	v_add_f32_dpp v92, v92, v92 row_half_mirror row_mask:0xf bank_mask:0xf bound_ctrl:1
	v_add_f32_e32 v96, v94, v95
	v_add_f32_dpp v100, v101, v100 quad_perm:[1,0,3,2] row_mask:0xf bank_mask:0xf bound_ctrl:1
	v_add_f32_dpp v92, v92, v92 row_mirror row_mask:0xf bank_mask:0xf bound_ctrl:1
	v_add_f32_dpp v103, v103, v102 quad_perm:[1,0,3,2] row_mask:0xf bank_mask:0xf bound_ctrl:1
	v_pk_fma_f32 v[0:1], v[28:29], v[92:93], v[86:87] op_sel_hi:[1,0,1]
	v_pk_fma_f32 v[2:3], v[30:31], v[92:93], v[88:89] op_sel_hi:[1,0,1]
	v_cndmask_b32_e64 v101, v103, v100, s[8:9]
	v_cndmask_b32_e64 v102, v100, v103, s[8:9]
	s_waitcnt lgkmcnt(5)
	v_pk_mul_f32 v[90:91], v[0:1], v[44:45]
	v_pk_fma_f32 v[86:87], v[52:53], v[78:79], v[0:1] op_sel_hi:[1,0,1]
	v_pk_fma_f32 v[90:91], v[2:3], v[46:47], v[90:91]
	v_pk_mul_f32 v[94:95], v[0:1], v[40:41]
	v_pk_fma_f32 v[88:89], v[54:55], v[78:79], v[2:3] op_sel_hi:[1,0,1]
	v_add_f32_e32 v92, v90, v91
	v_pk_fma_f32 v[94:95], v[2:3], v[42:43], v[94:95]
	ds_read_b128 v[24:27], v67 offset:37632
	v_add_f32_dpp v92, v92, v92 quad_perm:[1,0,3,2] row_mask:0xf bank_mask:0xf bound_ctrl:1
	ds_read_b128 v[32:35], v67 offset:38144
	ds_read_b128 v[28:31], v67 offset:37888
	v_add_f32_dpp v92, v92, v92 quad_perm:[2,3,0,1] row_mask:0xf bank_mask:0xf bound_ctrl:1
	ds_read_b128 v[40:43], v67 offset:38656
	ds_read_b32 v76, v85 offset:38912
	v_add_f32_dpp v92, v92, v92 row_half_mirror row_mask:0xf bank_mask:0xf bound_ctrl:1
	v_add_f32_e32 v97, v94, v95
	s_nop 0
	v_add_f32_dpp v92, v92, v92 row_mirror row_mask:0xf bank_mask:0xf bound_ctrl:1
	v_add_f32_dpp v102, v102, v101 quad_perm:[2,3,0,1] row_mask:0xf bank_mask:0xf bound_ctrl:1
	v_pk_fma_f32 v[0:1], v[48:49], v[92:93], v[86:87] op_sel_hi:[1,0,1]
	v_pk_fma_f32 v[2:3], v[50:51], v[92:93], v[88:89] op_sel_hi:[1,0,1]
	v_add_f32_dpp v102, v102, v102 row_ror:4 row_mask:0xf bank_mask:0xf bound_ctrl:1
	s_waitcnt lgkmcnt(5)
	v_pk_mul_f32 v[90:91], v[0:1], v[4:5]
	v_pk_fma_f32 v[86:87], v[12:13], v[74:75], v[0:1] op_sel_hi:[1,0,1]
	v_pk_fma_f32 v[90:91], v[2:3], v[6:7], v[90:91]
	v_pk_mul_f32 v[94:95], v[0:1], v[80:81]
	v_pk_fma_f32 v[88:89], v[14:15], v[74:75], v[2:3] op_sel_hi:[1,0,1]
	v_add_f32_e32 v92, v90, v91
	v_pk_fma_f32 v[94:95], v[2:3], v[82:83], v[94:95]
	ds_read_b128 v[44:47], v67 offset:38976
	v_add_f32_dpp v92, v92, v92 quad_perm:[1,0,3,2] row_mask:0xf bank_mask:0xf bound_ctrl:1
	ds_read_b128 v[52:55], v67 offset:39488
	ds_read_b128 v[48:51], v67 offset:39232
	v_add_f32_dpp v92, v92, v92 quad_perm:[2,3,0,1] row_mask:0xf bank_mask:0xf bound_ctrl:1
	ds_read_b128 v[80:83], v67 offset:40000
	ds_read_b32 v78, v85 offset:40256
	v_add_f32_dpp v92, v92, v92 row_half_mirror row_mask:0xf bank_mask:0xf bound_ctrl:1
	v_add_f32_e32 v98, v94, v95
	v_mov_b32_dpp v103, v102 row_ror:8 row_mask:0xf bank_mask:0xf bound_ctrl:1
	v_add_f32_dpp v92, v92, v92 row_mirror row_mask:0xf bank_mask:0xf bound_ctrl:1
	v_add_f32_e32 v100, v102, v103
	v_pk_fma_f32 v[0:1], v[8:9], v[92:93], v[86:87] op_sel_hi:[1,0,1]
	v_pk_fma_f32 v[2:3], v[10:11], v[92:93], v[88:89] op_sel_hi:[1,0,1]
	v_cvt_pk_bf16_f32 v100, v100, v100
	s_and_saveexec_b64 s[16:17], s[4:5]
	global_store_short v[72:73], v100, off
	s_or_b64 exec, exec, s[16:17]
	v_lshl_add_u64 v[72:73], v[72:73], 0, s[14:15]
	s_waitcnt lgkmcnt(5)
	v_pk_mul_f32 v[90:91], v[0:1], v[24:25]
	v_pk_fma_f32 v[86:87], v[32:33], v[76:77], v[0:1] op_sel_hi:[1,0,1]
	v_pk_fma_f32 v[90:91], v[2:3], v[26:27], v[90:91]
	v_pk_mul_f32 v[94:95], v[0:1], v[20:21]
	v_pk_fma_f32 v[88:89], v[34:35], v[76:77], v[2:3] op_sel_hi:[1,0,1]
	v_add_f32_e32 v92, v90, v91
	v_pk_fma_f32 v[94:95], v[2:3], v[22:23], v[94:95]
	ds_read_b128 v[4:7], v67 offset:40320
	v_add_f32_dpp v92, v92, v92 quad_perm:[1,0,3,2] row_mask:0xf bank_mask:0xf bound_ctrl:1
	ds_read_b128 v[12:15], v67 offset:40832
	ds_read_b128 v[8:11], v67 offset:40576
	v_add_f32_dpp v92, v92, v92 quad_perm:[2,3,0,1] row_mask:0xf bank_mask:0xf bound_ctrl:1
	ds_read_b128 v[20:23], v67 offset:41344
	ds_read_b32 v74, v85 offset:41600
	v_add_f32_dpp v92, v92, v92 row_half_mirror row_mask:0xf bank_mask:0xf bound_ctrl:1
	v_add_f32_e32 v99, v94, v95
	v_cndmask_b32_e64 v100, v98, v96, s[6:7]
	v_add_f32_dpp v92, v92, v92 row_mirror row_mask:0xf bank_mask:0xf bound_ctrl:1
	v_cndmask_b32_e64 v101, v96, v98, s[6:7]
	v_pk_fma_f32 v[0:1], v[28:29], v[92:93], v[86:87] op_sel_hi:[1,0,1]
	v_pk_fma_f32 v[2:3], v[30:31], v[92:93], v[88:89] op_sel_hi:[1,0,1]
	v_cndmask_b32_e64 v102, v99, v97, s[6:7]
	v_cndmask_b32_e64 v103, v97, v99, s[6:7]
	s_waitcnt lgkmcnt(5)
	v_pk_mul_f32 v[90:91], v[0:1], v[44:45]
	v_pk_fma_f32 v[86:87], v[52:53], v[78:79], v[0:1] op_sel_hi:[1,0,1]
	v_pk_fma_f32 v[90:91], v[2:3], v[46:47], v[90:91]
	v_pk_mul_f32 v[94:95], v[0:1], v[40:41]
	v_pk_fma_f32 v[88:89], v[54:55], v[78:79], v[2:3] op_sel_hi:[1,0,1]
	v_add_f32_e32 v92, v90, v91
	v_pk_fma_f32 v[94:95], v[2:3], v[42:43], v[94:95]
	ds_read_b128 v[24:27], v67 offset:41664
	v_add_f32_dpp v92, v92, v92 quad_perm:[1,0,3,2] row_mask:0xf bank_mask:0xf bound_ctrl:1
	ds_read_b128 v[32:35], v67 offset:42176
	ds_read_b128 v[28:31], v67 offset:41920
	v_add_f32_dpp v92, v92, v92 quad_perm:[2,3,0,1] row_mask:0xf bank_mask:0xf bound_ctrl:1
	ds_read_b128 v[40:43], v67 offset:42688
	ds_read_b32 v76, v85 offset:42944
	v_add_f32_dpp v92, v92, v92 row_half_mirror row_mask:0xf bank_mask:0xf bound_ctrl:1
	v_add_f32_e32 v96, v94, v95
	ds_read_b128 v[36:39], v67 offset:42432
	v_add_f32_dpp v92, v92, v92 row_mirror row_mask:0xf bank_mask:0xf bound_ctrl:1
	v_add_f32_dpp v100, v101, v100 quad_perm:[1,0,3,2] row_mask:0xf bank_mask:0xf bound_ctrl:1
	v_pk_fma_f32 v[0:1], v[48:49], v[92:93], v[86:87] op_sel_hi:[1,0,1]
	v_pk_fma_f32 v[2:3], v[50:51], v[92:93], v[88:89] op_sel_hi:[1,0,1]
	v_add_f32_dpp v103, v103, v102 quad_perm:[1,0,3,2] row_mask:0xf bank_mask:0xf bound_ctrl:1
	v_cndmask_b32_e64 v101, v103, v100, s[8:9]
	v_cndmask_b32_e64 v102, v100, v103, s[8:9]
	s_waitcnt lgkmcnt(6)
	v_pk_mul_f32 v[90:91], v[0:1], v[4:5]
	v_pk_fma_f32 v[86:87], v[12:13], v[74:75], v[0:1] op_sel_hi:[1,0,1]
	v_pk_fma_f32 v[90:91], v[2:3], v[6:7], v[90:91]
	v_pk_mul_f32 v[94:95], v[0:1], v[80:81]
	v_pk_fma_f32 v[88:89], v[14:15], v[74:75], v[2:3] op_sel_hi:[1,0,1]
	v_add_f32_e32 v92, v90, v91
	v_pk_fma_f32 v[94:95], v[2:3], v[82:83], v[94:95]
	s_nop 0
	v_add_f32_dpp v92, v92, v92 quad_perm:[1,0,3,2] row_mask:0xf bank_mask:0xf bound_ctrl:1
	s_nop 1
	v_add_f32_dpp v92, v92, v92 quad_perm:[2,3,0,1] row_mask:0xf bank_mask:0xf bound_ctrl:1
	s_nop 1
	v_add_f32_dpp v92, v92, v92 row_half_mirror row_mask:0xf bank_mask:0xf bound_ctrl:1
	v_add_f32_e32 v97, v94, v95
	s_nop 0
	v_add_f32_dpp v92, v92, v92 row_mirror row_mask:0xf bank_mask:0xf bound_ctrl:1
	v_add_f32_dpp v102, v102, v101 quad_perm:[2,3,0,1] row_mask:0xf bank_mask:0xf bound_ctrl:1
	v_pk_fma_f32 v[0:1], v[8:9], v[92:93], v[86:87] op_sel_hi:[1,0,1]
	v_pk_fma_f32 v[2:3], v[10:11], v[92:93], v[88:89] op_sel_hi:[1,0,1]
	v_add_f32_dpp v102, v102, v102 row_ror:4 row_mask:0xf bank_mask:0xf bound_ctrl:1
	s_waitcnt lgkmcnt(0)
	v_pk_mul_f32 v[90:91], v[0:1], v[24:25]
	v_pk_fma_f32 v[86:87], v[32:33], v[76:77], v[0:1] op_sel_hi:[1,0,1]
	v_pk_fma_f32 v[90:91], v[2:3], v[26:27], v[90:91]
	v_pk_mul_f32 v[94:95], v[0:1], v[20:21]
	v_pk_fma_f32 v[88:89], v[34:35], v[76:77], v[2:3] op_sel_hi:[1,0,1]
	v_add_f32_e32 v92, v90, v91
	v_pk_fma_f32 v[94:95], v[2:3], v[22:23], v[94:95]
	s_nop 0
	v_add_f32_dpp v92, v92, v92 quad_perm:[1,0,3,2] row_mask:0xf bank_mask:0xf bound_ctrl:1
	s_nop 1
	v_add_f32_dpp v92, v92, v92 quad_perm:[2,3,0,1] row_mask:0xf bank_mask:0xf bound_ctrl:1
	s_nop 1
	v_add_f32_dpp v92, v92, v92 row_half_mirror row_mask:0xf bank_mask:0xf bound_ctrl:1
	v_add_f32_e32 v98, v94, v95
	v_mov_b32_dpp v103, v102 row_ror:8 row_mask:0xf bank_mask:0xf bound_ctrl:1
	v_add_f32_dpp v92, v92, v92 row_mirror row_mask:0xf bank_mask:0xf bound_ctrl:1
	v_add_f32_e32 v100, v102, v103
	v_pk_fma_f32 v[0:1], v[28:29], v[92:93], v[86:87] op_sel_hi:[1,0,1]
	v_pk_fma_f32 v[2:3], v[30:31], v[92:93], v[88:89] op_sel_hi:[1,0,1]
	v_cvt_pk_bf16_f32 v100, v100, v100
	s_and_saveexec_b64 s[16:17], s[4:5]
	global_store_short v[72:73], v100, off
	s_or_b64 exec, exec, s[16:17]
	v_lshl_add_u64 v[72:73], v[72:73], 0, s[14:15]
	v_pk_mul_f32 v[94:95], v[0:1], v[40:41]
	v_pk_fma_f32 v[94:95], v[2:3], v[42:43], v[94:95]
	v_pk_mul_f32 v[0:1], v[0:1], v[36:37]
	v_pk_mul_f32 v[2:3], v[2:3], v[38:39]
	v_add_f32_e32 v99, v94, v95
	v_cndmask_b32_e64 v100, v98, v96, s[6:7]
	v_cndmask_b32_e64 v101, v96, v98, s[6:7]
	v_cndmask_b32_e64 v102, v99, v97, s[6:7]
	v_cndmask_b32_e64 v103, v97, v99, s[6:7]
	v_add_f32_dpp v100, v101, v100 quad_perm:[1,0,3,2] row_mask:0xf bank_mask:0xf bound_ctrl:1
	s_nop 0
	v_add_f32_dpp v103, v103, v102 quad_perm:[1,0,3,2] row_mask:0xf bank_mask:0xf bound_ctrl:1
	v_cndmask_b32_e64 v101, v103, v100, s[8:9]
	v_cndmask_b32_e64 v102, v100, v103, s[8:9]
	s_nop 1
	v_add_f32_dpp v102, v102, v101 quad_perm:[2,3,0,1] row_mask:0xf bank_mask:0xf bound_ctrl:1
	s_nop 1
	v_add_f32_dpp v102, v102, v102 row_ror:4 row_mask:0xf bank_mask:0xf bound_ctrl:1
	s_nop 1
	v_mov_b32_dpp v103, v102 row_ror:8 row_mask:0xf bank_mask:0xf bound_ctrl:1
	v_add_f32_e32 v100, v102, v103
	v_cvt_pk_bf16_f32 v100, v100, v100
	s_and_saveexec_b64 s[16:17], s[4:5]
	global_store_short v[72:73], v100, off
	s_or_b64 exec, exec, s[16:17]
	v_lshl_add_u64 v[72:73], v[72:73], 0, s[14:15]
	s_branch .LBB0_1334

.LBB0_1450:
	s_ashr_i32 s3, s2, 31
	s_lshl_b64 s[14:15], s[2:3], 11
	v_lshl_add_u64 v[14:15], v[0:1], 0, s[14:15]
	global_load_ushort v13, v[14:15], off
	v_lshl_add_u64 v[14:15], v[2:3], 0, s[14:15]
	s_lshl_b64 s[2:3], s[2:3], 6
	global_load_ushort v16, v[14:15], off
	v_lshl_add_u64 v[14:15], v[6:7], 0, s[14:15]
	v_lshl_add_u64 v[68:69], v[8:9], 0, s[14:15]
	s_add_u32 s2, s65, s2
	global_load_ushort v15, v[14:15], off
	s_addc_u32 s3, s66, s3
	global_load_ushort v17, v[68:69], off
	v_lshl_add_u64 v[68:69], v[4:5], 0, s[14:15]
	global_load_ushort v14, v[68:69], off
	global_load_dword v19, v153, s[2:3]
	s_waitcnt vmcnt(46)
	v_cvt_f32_f16_e32 v58, v58
	s_waitcnt vmcnt(44)
	v_cvt_f32_f16_e32 v68, v59
	v_cvt_f32_f16_e32 v56, v56
	s_waitcnt vmcnt(42)
	v_mul_f32_e32 v59, v10, v67
	v_cvt_f32_f16_e32 v57, v57
	v_mul_f32_e32 v67, v59, v58
	v_add_f32_e32 v59, -1.0, v68
	v_fma_f32 v59, v12, v59, 1.0
	v_mul_f32_e32 v58, v59, v58
	v_add_u32_e32 v59, s90, v84
	v_mul_f32_e64 v68, v67, -v68
	v_sub_f32_e32 v56, 1.0, v56
	v_mov_b32_e32 v104, 1.0
	v_mul_f32_e32 v105, v67, v104
	v_mov_b32_e32 v106, v68
	v_mul_f32_e32 v104, v104, v56
	v_rcp_f32_e32 v107, v104
	s_nop 0
	v_mul_f32_e32 v106, v106, v107
	v_mul_f32_e32 v108, v58, v107
	ds_write2st64_b32 v59, v105, v106 offset1:1
	ds_write2st64_b32 v59, v108, v104 offset0:2 offset1:3
	v_mul_f32_e32 v107, v57, v104
	ds_write_b32 v59, v107 offset:1024
	s_and_saveexec_b64 s[2:3], s[10:11]
	v_cvt_f32_f16_e32 v55, v55
	ds_write_b32 v59, v55 offset:1280
	s_or_b64 exec, exec, s[2:3]
	s_and_b64 s[2:3], s[56:57], exec
	s_mov_b32 s2, 0x15af8000
	s_cselect_b32 s2, s2, 0x15d0e000
	s_add_u32 s14, s18, s2
	s_addc_u32 s15, s19, 0
	s_cmp_eq_u32 s58, 0
	s_cselect_b64 s[2:3], -1, 0
	s_add_u32 s76, s14, s33
	s_addc_u32 s64, s15, 0
	s_cmp_lg_u32 s58, 0
	s_cbranch_scc1 .LBB0_1467
	v_mul_f32_e32 v55, v58, v57
	v_mul_f32_e32 v56, v11, v55
	s_nop 1
	v_mov_b32_dpp v56, v56 quad_perm:[1,0,3,2] row_mask:0xf bank_mask:0xf bound_ctrl:1
	v_fmac_f32_e32 v56, v11, v55
	s_nop 1
	v_add_f32_dpp v55, v56, v56 quad_perm:[2,3,0,1] row_mask:0xf bank_mask:0xf bound_ctrl:1
	s_nop 1
	v_add_f32_dpp v55, v55, v55 row_half_mirror row_mask:0xf bank_mask:0xf bound_ctrl:1
	s_nop 1
	v_add_f32_dpp v55, v55, v55 row_mirror row_mask:0xf bank_mask:0xf bound_ctrl:1
	v_mov_b32_e32 v56, v55
	s_nop 1
	v_permlane16_swap_b32 v55, v56
	s_nop 1
	s_nop 0
	v_add_f32_e32 v55, v55, v56
	v_mov_b32_e32 v56, v55
	s_nop 1
	v_permlane32_swap_b32 v55, v56
	s_nop 1
	s_and_saveexec_b64 s[14:15], s[12:13]
	s_cbranch_execz .LBB0_1466
	s_mov_b64 s[60:61], -1
	s_and_b64 vcc, exec, s[22:23]
	s_cbranch_vccz .LBB0_1460
	s_andn2_b64 vcc, exec, s[0:1]
	s_cbranch_vccnz .LBB0_1457
	s_sub_i32 s58, s44, s75
	s_mov_b64 s[60:61], 0

.LBB0_1467:
	s_waitcnt vmcnt(38)
	v_cvt_f32_f16_e32 v53, v53
	v_cvt_f32_f16_e32 v52, v52
	s_waitcnt vmcnt(36)
	v_mul_f32_e32 v54, v10, v54
	v_cvt_f32_f16_e32 v49, v49
	v_add_f32_e32 v55, -1.0, v53
	v_fma_f32 v55, v12, v55, 1.0
	v_mul_f32_e32 v54, v54, v52
	v_mul_f32_e32 v52, v55, v52
	v_cvt_f32_f16_e32 v55, v51
	v_add_u32_e32 v51, s43, v84
	v_mul_f32_e64 v53, v54, -v53
	v_mul_f32_e32 v105, v54, v104
	v_mov_b32_e32 v106, v53
	v_sub_f32_e32 v53, 1.0, v55
	v_mul_f32_e32 v104, v104, v53
	v_rcp_f32_e32 v107, v104
	s_nop 0
	v_mul_f32_e32 v106, v106, v107
	v_mul_f32_e32 v108, v52, v107
	ds_write2st64_b32 v51, v105, v106 offset1:1
	ds_write2st64_b32 v51, v108, v104 offset0:2 offset1:3
	v_mul_f32_e32 v107, v49, v104
	ds_write_b32 v51, v107 offset:1024
	s_and_saveexec_b64 s[14:15], s[10:11]
	v_cvt_f32_f16_e32 v50, v50
	ds_write_b32 v51, v50 offset:1280
	s_or_b64 exec, exec, s[14:15]
	v_cndmask_b32_e64 v50, 0, 1, s[2:3]
	v_cmp_ne_u32_e64 s[14:15], 1, v50
	s_andn2_b64 vcc, exec, s[2:3]
	s_cbranch_vccnz .LBB0_1484
	v_mul_f32_e32 v49, v52, v49
	v_mul_f32_e32 v50, v11, v49
	s_nop 1
	v_mov_b32_dpp v50, v50 quad_perm:[1,0,3,2] row_mask:0xf bank_mask:0xf bound_ctrl:1
	v_fmac_f32_e32 v50, v11, v49
	s_nop 1
	v_add_f32_dpp v49, v50, v50 quad_perm:[2,3,0,1] row_mask:0xf bank_mask:0xf bound_ctrl:1
	s_nop 1
	v_add_f32_dpp v49, v49, v49 row_half_mirror row_mask:0xf bank_mask:0xf bound_ctrl:1
	s_nop 1
	v_add_f32_dpp v49, v49, v49 row_mirror row_mask:0xf bank_mask:0xf bound_ctrl:1
	v_mov_b32_e32 v50, v49
	s_nop 1
	v_permlane16_swap_b32 v49, v50
	s_nop 1
	s_nop 0
	v_add_f32_e32 v49, v49, v50
	v_mov_b32_e32 v50, v49
	s_nop 1
	v_permlane32_swap_b32 v49, v50
	s_nop 1
	s_and_saveexec_b64 s[2:3], s[12:13]
	s_cbranch_execz .LBB0_1483
	s_and_b64 vcc, exec, s[16:17]
	s_mov_b64 s[60:61], -1
	s_cbranch_vccnz .LBB0_1477
	s_andn2_b64 vcc, exec, s[0:1]
	s_cbranch_vccnz .LBB0_1474
	s_sub_i32 s58, s44, s83
	s_mov_b64 s[60:61], 0

.LBB0_1484:
	s_waitcnt vmcnt(34)
	v_cvt_f32_f16_e32 v46, v46
	s_waitcnt vmcnt(32)
	v_cvt_f32_f16_e32 v49, v47
	s_waitcnt vmcnt(30)
	v_mul_f32_e32 v47, v10, v48
	v_cvt_f32_f16_e32 v45, v45
	v_mul_f32_e32 v48, v47, v46
	v_add_f32_e32 v47, -1.0, v49
	v_fma_f32 v47, v12, v47, 1.0
	v_mul_f32_e32 v46, v47, v46
	v_cvt_f32_f16_e32 v47, v43
	v_add_u32_e32 v43, s45, v84
	v_mul_f32_e64 v49, v48, -v49
	v_sub_f32_e32 v45, 1.0, v45
	v_mul_f32_e32 v105, v48, v104
	v_mov_b32_e32 v106, v49
	v_mul_f32_e32 v104, v104, v45
	v_rcp_f32_e32 v107, v104
	s_nop 0
	v_mul_f32_e32 v106, v106, v107
	v_mul_f32_e32 v108, v46, v107
	ds_write2st64_b32 v43, v105, v106 offset1:1
	ds_write2st64_b32 v43, v108, v104 offset0:2 offset1:3
	v_mul_f32_e32 v107, v47, v104
	ds_write_b32 v43, v107 offset:1024
	s_and_saveexec_b64 s[2:3], s[10:11]
	v_cvt_f32_f16_e32 v44, v44
	ds_write_b32 v43, v44 offset:1280
	s_or_b64 exec, exec, s[2:3]
	s_and_b64 vcc, exec, s[14:15]
	s_cbranch_vccnz .LBB0_1501
	v_mul_f32_e32 v44, v46, v47
	v_mul_f32_e32 v45, v11, v44
	s_nop 1
	v_mov_b32_dpp v45, v45 quad_perm:[1,0,3,2] row_mask:0xf bank_mask:0xf bound_ctrl:1
	v_fmac_f32_e32 v45, v11, v44
	s_nop 1
	v_add_f32_dpp v44, v45, v45 quad_perm:[2,3,0,1] row_mask:0xf bank_mask:0xf bound_ctrl:1
	s_nop 1
	v_add_f32_dpp v44, v44, v44 row_half_mirror row_mask:0xf bank_mask:0xf bound_ctrl:1
	s_nop 1
	v_add_f32_dpp v44, v44, v44 row_mirror row_mask:0xf bank_mask:0xf bound_ctrl:1
	v_mov_b32_e32 v45, v44
	s_nop 1
	v_permlane16_swap_b32 v44, v45
	s_nop 1
	s_nop 0
	v_add_f32_e32 v44, v44, v45
	v_mov_b32_e32 v45, v44
	s_nop 1
	v_permlane32_swap_b32 v44, v45
	s_nop 1
	s_and_saveexec_b64 s[2:3], s[12:13]
	s_cbranch_execz .LBB0_1500
	s_and_b64 vcc, exec, s[16:17]
	s_mov_b64 s[60:61], -1
	s_cbranch_vccnz .LBB0_1494
	s_andn2_b64 vcc, exec, s[0:1]
	s_cbranch_vccnz .LBB0_1491
	s_sub_i32 s58, s44, s84
	s_mov_b64 s[60:61], 0

.LBB0_1501:
	s_waitcnt vmcnt(28)
	v_cvt_f32_f16_e32 v40, v40
	s_waitcnt vmcnt(26)
	v_cvt_f32_f16_e32 v44, v41
	s_waitcnt vmcnt(24)
	v_mul_f32_e32 v41, v10, v42
	v_cvt_f32_f16_e32 v39, v39
	v_mul_f32_e32 v42, v41, v40
	v_add_f32_e32 v41, -1.0, v44
	v_fma_f32 v41, v12, v41, 1.0
	v_mul_f32_e32 v40, v41, v40
	v_cvt_f32_f16_e32 v41, v37
	v_mul_f32_e64 v44, v42, -v44
	v_add_u32_e32 v37, 64, v43
	v_sub_f32_e32 v39, 1.0, v39
	v_mul_f32_e32 v105, v42, v104
	v_mov_b32_e32 v106, v44
	v_mul_f32_e32 v104, v104, v39
	v_rcp_f32_e32 v107, v104
	s_nop 0
	v_mul_f32_e32 v106, v106, v107
	v_mul_f32_e32 v108, v40, v107
	ds_write2st64_b32 v37, v105, v106 offset0:5 offset1:6
	ds_write2st64_b32 v37, v108, v104 offset0:7 offset1:8
	v_mul_f32_e32 v107, v41, v104
	ds_write_b32 v43, v107 offset:2368
	s_and_saveexec_b64 s[2:3], s[10:11]
	v_cvt_f32_f16_e32 v38, v38
	ds_write_b32 v43, v38 offset:2624
	s_or_b64 exec, exec, s[2:3]
	s_and_b64 vcc, exec, s[14:15]
	s_cbranch_vccnz .LBB0_1518
	v_mul_f32_e32 v38, v40, v41
	v_mul_f32_e32 v39, v11, v38
	s_nop 1
	v_mov_b32_dpp v39, v39 quad_perm:[1,0,3,2] row_mask:0xf bank_mask:0xf bound_ctrl:1
	v_fmac_f32_e32 v39, v11, v38
	s_nop 1
	v_add_f32_dpp v38, v39, v39 quad_perm:[2,3,0,1] row_mask:0xf bank_mask:0xf bound_ctrl:1
	s_nop 1
	v_add_f32_dpp v38, v38, v38 row_half_mirror row_mask:0xf bank_mask:0xf bound_ctrl:1
	s_nop 1
	v_add_f32_dpp v38, v38, v38 row_mirror row_mask:0xf bank_mask:0xf bound_ctrl:1
	v_mov_b32_e32 v39, v38
	s_nop 1
	v_permlane16_swap_b32 v39, v38
	s_nop 1
	s_nop 0
	v_add_f32_e32 v38, v39, v38
	v_mov_b32_e32 v39, v38
	s_nop 1
	v_permlane32_swap_b32 v39, v38
	s_nop 1
	s_and_saveexec_b64 s[2:3], s[12:13]
	s_cbranch_execz .LBB0_1517
	s_and_b64 vcc, exec, s[16:17]
	s_mov_b64 s[60:61], -1
	s_cbranch_vccnz .LBB0_1511
	s_andn2_b64 vcc, exec, s[0:1]
	s_cbranch_vccnz .LBB0_1508
	s_sub_i32 s58, s44, s85
	s_mov_b64 s[60:61], 0

.LBB0_1518:
	s_waitcnt vmcnt(20)
	v_cvt_f32_f16_e32 v35, v35
	v_cvt_f32_f16_e32 v34, v34
	v_cvt_f32_f16_e32 v33, v33
	v_cvt_f32_f16_e32 v31, v31
	s_waitcnt vmcnt(18)
	v_mul_f32_e32 v36, v10, v36
	v_add_f32_e32 v38, -1.0, v35
	v_mul_f32_e32 v36, v36, v34
	v_fma_f32 v38, v12, v38, 1.0
	v_mul_f32_e32 v34, v38, v34
	v_mul_f32_e64 v35, v36, -v35
	v_add_u32_e32 v38, 0x80, v43
	v_sub_f32_e32 v33, 1.0, v33
	v_mul_f32_e32 v105, v36, v104
	v_mov_b32_e32 v106, v35
	v_mul_f32_e32 v104, v104, v33
	v_rcp_f32_e32 v107, v104
	s_nop 0
	v_mul_f32_e32 v106, v106, v107
	v_mul_f32_e32 v108, v34, v107
	ds_write2st64_b32 v38, v105, v106 offset0:10 offset1:11
	ds_write2st64_b32 v38, v108, v104 offset0:12 offset1:13
	v_mul_f32_e32 v107, v31, v104
	ds_write_b32 v43, v107 offset:3712
	s_and_saveexec_b64 s[2:3], s[10:11]
	v_cvt_f32_f16_e32 v32, v32
	ds_write_b32 v43, v32 offset:3968
	s_or_b64 exec, exec, s[2:3]
	s_and_b64 vcc, exec, s[14:15]
	s_cbranch_vccnz .LBB0_1535
	v_mul_f32_e32 v31, v34, v31
	v_mul_f32_e32 v32, v11, v31
	s_nop 1
	v_mov_b32_dpp v32, v32 quad_perm:[1,0,3,2] row_mask:0xf bank_mask:0xf bound_ctrl:1
	v_fmac_f32_e32 v32, v11, v31
	s_nop 1
	v_add_f32_dpp v31, v32, v32 quad_perm:[2,3,0,1] row_mask:0xf bank_mask:0xf bound_ctrl:1
	s_nop 1
	v_add_f32_dpp v31, v31, v31 row_half_mirror row_mask:0xf bank_mask:0xf bound_ctrl:1
	s_nop 1
	v_add_f32_dpp v31, v31, v31 row_mirror row_mask:0xf bank_mask:0xf bound_ctrl:1
	v_mov_b32_e32 v32, v31
	s_nop 1
	v_permlane16_swap_b32 v31, v32
	s_nop 1
	s_nop 0
	v_add_f32_e32 v31, v31, v32
	v_mov_b32_e32 v32, v31
	s_nop 1
	v_permlane32_swap_b32 v31, v32
	s_nop 1
	s_and_saveexec_b64 s[2:3], s[12:13]
	s_cbranch_execz .LBB0_1534
	s_and_b64 vcc, exec, s[16:17]
	s_mov_b64 s[60:61], -1
	s_cbranch_vccnz .LBB0_1528
	s_andn2_b64 vcc, exec, s[0:1]
	s_cbranch_vccnz .LBB0_1525
	s_sub_i32 s58, s44, s86
	s_mov_b64 s[60:61], 0

.LBB0_1535:
	s_waitcnt vmcnt(14)
	v_cvt_f32_f16_e32 v29, v29
	v_cvt_f32_f16_e32 v28, v28
	v_cvt_f32_f16_e32 v27, v27
	v_cvt_f32_f16_e32 v25, v25
	s_waitcnt vmcnt(12)
	v_mul_f32_e32 v30, v10, v30
	v_add_f32_e32 v31, -1.0, v29
	v_mul_f32_e32 v30, v30, v28
	v_fma_f32 v31, v12, v31, 1.0
	v_mul_f32_e32 v28, v31, v28
	v_mul_f32_e64 v29, v30, -v29
	v_add_u32_e32 v31, 0xc0, v43
	v_sub_f32_e32 v27, 1.0, v27
	v_mul_f32_e32 v105, v30, v104
	v_mov_b32_e32 v106, v29
	v_mul_f32_e32 v104, v104, v27
	v_rcp_f32_e32 v107, v104
	s_nop 0
	v_mul_f32_e32 v106, v106, v107
	v_mul_f32_e32 v108, v28, v107
	ds_write2st64_b32 v31, v105, v106 offset0:15 offset1:16
	ds_write2st64_b32 v31, v108, v104 offset0:17 offset1:18
	v_mul_f32_e32 v107, v25, v104
	ds_write_b32 v43, v107 offset:5056
	s_and_saveexec_b64 s[2:3], s[10:11]
	v_cvt_f32_f16_e32 v26, v26
	ds_write_b32 v43, v26 offset:5312
	s_or_b64 exec, exec, s[2:3]
	s_and_b64 vcc, exec, s[14:15]
	s_cbranch_vccnz .LBB0_1552
	v_mul_f32_e32 v25, v28, v25
	v_mul_f32_e32 v26, v11, v25
	s_nop 1
	v_mov_b32_dpp v26, v26 quad_perm:[1,0,3,2] row_mask:0xf bank_mask:0xf bound_ctrl:1
	v_fmac_f32_e32 v26, v11, v25
	s_nop 1
	v_add_f32_dpp v25, v26, v26 quad_perm:[2,3,0,1] row_mask:0xf bank_mask:0xf bound_ctrl:1
	s_nop 1
	v_add_f32_dpp v25, v25, v25 row_half_mirror row_mask:0xf bank_mask:0xf bound_ctrl:1
	s_nop 1
	v_add_f32_dpp v25, v25, v25 row_mirror row_mask:0xf bank_mask:0xf bound_ctrl:1
	v_mov_b32_e32 v26, v25
	s_nop 1
	v_permlane16_swap_b32 v25, v26
	s_nop 1
	s_nop 0
	v_add_f32_e32 v25, v25, v26
	v_mov_b32_e32 v26, v25
	s_nop 1
	v_permlane32_swap_b32 v25, v26
	s_nop 1
	s_and_saveexec_b64 s[2:3], s[12:13]
	s_cbranch_execz .LBB0_1551
	s_and_b64 vcc, exec, s[16:17]
	s_mov_b64 s[60:61], -1
	s_cbranch_vccnz .LBB0_1545
	s_andn2_b64 vcc, exec, s[0:1]
	s_cbranch_vccnz .LBB0_1542
	s_sub_i32 s58, s44, s87
	s_mov_b64 s[60:61], 0

.LBB0_1552:
	s_waitcnt vmcnt(8)
	v_cvt_f32_f16_e32 v23, v23
	v_cvt_f32_f16_e32 v22, v22
	v_cvt_f32_f16_e32 v21, v21
	v_cvt_f32_f16_e32 v18, v18
	s_waitcnt vmcnt(6)
	v_mul_f32_e32 v24, v10, v24
	v_add_f32_e32 v25, -1.0, v23
	v_mul_f32_e32 v24, v24, v22
	v_fma_f32 v25, v12, v25, 1.0
	v_mul_f32_e32 v22, v25, v22
	v_mul_f32_e64 v23, v24, -v23
	v_sub_f32_e32 v21, 1.0, v21
	v_mul_f32_e32 v105, v24, v104
	v_mov_b32_e32 v106, v23
	v_mul_f32_e32 v104, v104, v21
	v_rcp_f32_e32 v107, v104
	s_nop 0
	v_mul_f32_e32 v106, v106, v107
	v_mul_f32_e32 v108, v22, v107
	ds_write2st64_b32 v43, v105, v106 offset0:21 offset1:22
	ds_write2st64_b32 v43, v108, v104 offset0:23 offset1:24
	v_mul_f32_e32 v107, v18, v104
	ds_write_b32 v43, v107 offset:6400
	s_and_saveexec_b64 s[2:3], s[10:11]
	v_cvt_f32_f16_e32 v20, v20
	ds_write_b32 v43, v20 offset:6656
	s_or_b64 exec, exec, s[2:3]
	s_and_b64 vcc, exec, s[14:15]
	s_cbranch_vccnz .LBB0_1569
	v_mul_f32_e32 v18, v22, v18
	v_mul_f32_e32 v20, v11, v18
	s_nop 1
	v_mov_b32_dpp v20, v20 quad_perm:[1,0,3,2] row_mask:0xf bank_mask:0xf bound_ctrl:1
	v_fmac_f32_e32 v20, v11, v18
	s_nop 1
	v_add_f32_dpp v18, v20, v20 quad_perm:[2,3,0,1] row_mask:0xf bank_mask:0xf bound_ctrl:1
	s_nop 1
	v_add_f32_dpp v18, v18, v18 row_half_mirror row_mask:0xf bank_mask:0xf bound_ctrl:1
	s_nop 1
	v_add_f32_dpp v18, v18, v18 row_mirror row_mask:0xf bank_mask:0xf bound_ctrl:1
	v_mov_b32_e32 v20, v18
	s_nop 1
	v_permlane16_swap_b32 v18, v20
	s_nop 1
	s_nop 0
	v_add_f32_e32 v18, v18, v20
	v_mov_b32_e32 v20, v18
	s_nop 1
	v_permlane32_swap_b32 v18, v20
	s_nop 1
	s_and_saveexec_b64 s[2:3], s[12:13]
	s_cbranch_execz .LBB0_1568
	s_and_b64 vcc, exec, s[16:17]
	s_mov_b64 s[60:61], -1
	s_cbranch_vccnz .LBB0_1562
	s_andn2_b64 vcc, exec, s[0:1]
	s_cbranch_vccnz .LBB0_1559
	s_sub_i32 s58, s44, s95
	s_mov_b64 s[60:61], 0

.LBB0_1569:
	s_waitcnt vmcnt(2)
	v_cvt_f32_f16_e32 v17, v17
	v_cvt_f32_f16_e32 v16, v16
	v_cvt_f32_f16_e32 v15, v15
	v_cvt_f32_f16_e32 v13, v13
	s_waitcnt vmcnt(0)
	v_mul_f32_e32 v18, v10, v19
	v_add_f32_e32 v19, -1.0, v17
	v_mul_f32_e32 v18, v18, v16
	v_fma_f32 v19, v12, v19, 1.0
	v_mul_f32_e32 v16, v19, v16
	v_mul_f32_e64 v17, v18, -v17
	v_sub_f32_e32 v15, 1.0, v15
	v_mul_f32_e32 v105, v18, v104
	v_mov_b32_e32 v106, v17
	v_mul_f32_e32 v104, v104, v15
	v_rcp_f32_e32 v107, v104
	s_nop 0
	v_mul_f32_e32 v106, v106, v107
	v_mul_f32_e32 v108, v16, v107
	ds_write2st64_b32 v37, v105, v106 offset0:26 offset1:27
	ds_write2st64_b32 v37, v108, v104 offset0:28 offset1:29
	v_mul_f32_e32 v107, v13, v104
	ds_write_b32 v43, v107 offset:7744
	s_and_saveexec_b64 s[2:3], s[10:11]
	s_cbranch_execz .LBB0_1586
	v_cvt_f32_f16_e32 v14, v14
	ds_write_b32 v43, v14 offset:8000
	s_or_b64 exec, exec, s[2:3]
	s_and_b64 vcc, exec, s[14:15]
	s_cbranch_vccnz .LBB0_1587

.LBB0_1763:
	s_ashr_i32 s3, s2, 31
	s_lshl_b64 s[16:17], s[2:3], 11
	v_lshl_add_u64 v[14:15], v[0:1], 0, s[16:17]
	global_load_ushort v13, v[14:15], off
	v_lshl_add_u64 v[14:15], v[2:3], 0, s[16:17]
	global_load_ushort v17, v[14:15], off
	v_lshl_add_u64 v[14:15], v[6:7], 0, s[16:17]
	s_lshl_b64 s[2:3], s[2:3], 6
	global_load_ushort v16, v[14:15], off
	v_lshl_add_u64 v[14:15], v[8:9], 0, s[16:17]
	s_add_u32 s2, s65, s2
	global_load_ushort v18, v[14:15], off
	v_lshl_add_u64 v[14:15], v[4:5], 0, s[16:17]
	s_addc_u32 s3, s66, s3
	global_load_ushort v15, v[14:15], off
	v_cvt_f32_f16_e32 v100, v96
	global_load_dword v14, v153, s[2:3]
	v_cvt_f32_f16_e32 v102, v99
	s_add_i32 s80, s61, 32
	s_and_b32 s2, s80, 32
	v_mul_f32_e32 v85, v10, v85
	s_add_i32 s2, s2, s75
	v_mul_f32_e32 v103, v85, v100
	v_add_f32_e32 v85, -1.0, v102
	s_mulk_i32 s2, 0x540
	v_fma_f32 v85, v12, v85, 1.0
	v_mul_f32_e32 v100, v85, v100
	v_add_u32_e32 v85, s2, v84
	v_mul_f32_e64 v102, v103, -v102
	v_mov_b32_e32 v104, 1.0
	v_mul_f32_e32 v105, v103, v104
	v_mov_b32_e32 v106, v102
	v_cvt_f32_f16_e32 v102, v97
	v_cvt_f32_f16_e32 v101, v95
	v_sub_f32_e32 v102, 1.0, v102
	v_mul_f32_e32 v104, v104, v102
	v_rcp_f32_e32 v107, v104
	s_nop 0
	v_mul_f32_e32 v106, v106, v107
	v_mul_f32_e32 v108, v100, v107
	ds_write2st64_b32 v85, v105, v106 offset1:1
	ds_write2st64_b32 v85, v108, v104 offset0:2 offset1:3
	v_mul_f32_e32 v107, v101, v104
	ds_write_b32 v85, v107 offset:1024
	s_and_saveexec_b64 s[2:3], s[10:11]
	v_cvt_f32_f16_e32 v102, v98
	ds_write_b32 v85, v102 offset:1280
	s_or_b64 exec, exec, s[2:3]
	s_add_i32 s60, s60, 1
	s_lshl_b32 s82, s60, 5
	s_and_b64 vcc, exec, s[14:15]
	s_add_i32 s82, s82, s75
	s_and_b32 s2, s55, 3
	s_cmp_lg_u32 s2, 0
	s_cbranch_scc1 .LBB0_1780
	v_mul_f32_e32 v100, v100, v101
	v_mul_f32_e32 v101, v11, v100
	s_nop 1
	v_mov_b32_dpp v101, v101 quad_perm:[1,0,3,2] row_mask:0xf bank_mask:0xf bound_ctrl:1
	v_fmac_f32_e32 v101, v11, v100
	s_nop 1
	v_add_f32_dpp v100, v101, v101 quad_perm:[2,3,0,1] row_mask:0xf bank_mask:0xf bound_ctrl:1
	s_nop 1
	v_add_f32_dpp v100, v100, v100 row_half_mirror row_mask:0xf bank_mask:0xf bound_ctrl:1
	s_nop 1
	v_add_f32_dpp v100, v100, v100 row_mirror row_mask:0xf bank_mask:0xf bound_ctrl:1
	v_mov_b32_e32 v101, v100
	s_nop 1
	v_permlane16_swap_b32 v100, v101
	s_nop 1
	s_nop 0
	v_add_f32_e32 v100, v100, v101
	v_mov_b32_e32 v101, v100
	s_nop 1
	v_permlane32_swap_b32 v100, v101
	s_nop 1
	s_and_saveexec_b64 s[2:3], s[12:13]
	s_cbranch_execz .LBB0_1779
	s_cmpk_gt_i32 s67, 0xff
	s_mov_b64 s[58:59], -1
	s_cbranch_scc0 .LBB0_1773
	s_andn2_b64 vcc, exec, s[0:1]
	s_cbranch_vccnz .LBB0_1770
	s_sub_i32 s16, s44, s82
	s_mov_b64 s[58:59], 0

.LBB0_1780:
	v_cvt_f32_f16_sdwa v96, v96 dst_sel:DWORD dst_unused:UNUSED_PAD src0_sel:WORD_1
	v_cvt_f32_f16_sdwa v99, v99 dst_sel:DWORD dst_unused:UNUSED_PAD src0_sel:WORD_1
	v_cvt_f32_f16_sdwa v97, v97 dst_sel:DWORD dst_unused:UNUSED_PAD src0_sel:WORD_1
	v_mul_f32_e32 v82, v10, v82
	v_cvt_f32_f16_sdwa v95, v95 dst_sel:DWORD dst_unused:UNUSED_PAD src0_sel:WORD_1
	v_mul_f32_e32 v100, v82, v96
	v_add_f32_e32 v82, -1.0, v99
	v_fma_f32 v82, v12, v82, 1.0
	v_mul_f32_e32 v96, v82, v96
	v_mul_f32_e64 v99, v100, -v99
	v_add_u32_e32 v82, 64, v85
	v_sub_f32_e32 v97, 1.0, v97
	v_mul_f32_e32 v105, v100, v104
	v_mov_b32_e32 v106, v99
	v_mul_f32_e32 v104, v104, v97
	v_rcp_f32_e32 v107, v104
	s_nop 0
	v_mul_f32_e32 v106, v106, v107
	v_mul_f32_e32 v108, v96, v107
	ds_write2st64_b32 v82, v105, v106 offset0:5 offset1:6
	ds_write2st64_b32 v82, v108, v104 offset0:7 offset1:8
	v_mul_f32_e32 v107, v95, v104
	ds_write_b32 v85, v107 offset:2368
	s_and_saveexec_b64 s[2:3], s[10:11]
	v_cvt_f32_f16_sdwa v97, v98 dst_sel:DWORD dst_unused:UNUSED_PAD src0_sel:WORD_1
	ds_write_b32 v85, v97 offset:2624
	s_or_b64 exec, exec, s[2:3]
	s_and_b64 vcc, exec, s[14:15]
	s_and_b32 s2, s55, 3
	s_cmp_lg_u32 s2, 1
	s_cbranch_scc1 .LBB0_1797
	v_mul_f32_e32 v95, v96, v95
	v_mul_f32_e32 v96, v11, v95
	s_nop 1
	v_mov_b32_dpp v96, v96 quad_perm:[1,0,3,2] row_mask:0xf bank_mask:0xf bound_ctrl:1
	v_fmac_f32_e32 v96, v11, v95
	s_nop 1
	v_add_f32_dpp v95, v96, v96 quad_perm:[2,3,0,1] row_mask:0xf bank_mask:0xf bound_ctrl:1
	s_nop 1
	v_add_f32_dpp v95, v95, v95 row_half_mirror row_mask:0xf bank_mask:0xf bound_ctrl:1
	s_nop 1
	v_add_f32_dpp v95, v95, v95 row_mirror row_mask:0xf bank_mask:0xf bound_ctrl:1
	v_mov_b32_e32 v96, v95
	s_nop 1
	v_permlane16_swap_b32 v95, v96
	s_nop 1
	s_nop 0
	v_add_f32_e32 v95, v95, v96
	v_mov_b32_e32 v96, v95
	s_nop 1
	v_permlane32_swap_b32 v95, v96
	s_nop 1
	s_and_saveexec_b64 s[2:3], s[12:13]
	s_cbranch_execz .LBB0_1796
	s_or_b32 s17, s82, 1
	s_add_i32 s16, s67, 1
	s_cmpk_lt_i32 s16, 0x100
	s_mov_b64 s[58:59], -1
	s_cbranch_scc1 .LBB0_1790
	s_andn2_b64 vcc, exec, s[0:1]
	s_cbranch_vccnz .LBB0_1787
	s_sub_i32 s16, s44, s17
	s_mov_b64 s[58:59], 0

.LBB0_1797:
	v_cvt_f32_f16_e32 v95, v91
	v_cvt_f32_f16_e32 v97, v94
	v_mul_f32_e32 v81, v10, v81
	v_cvt_f32_f16_e32 v96, v90
	v_mul_f32_e32 v98, v81, v95
	v_add_f32_e32 v81, -1.0, v97
	v_fma_f32 v81, v12, v81, 1.0
	v_mul_f32_e32 v95, v81, v95
	v_mul_f32_e64 v97, v98, -v97
	v_add_u32_e32 v81, 0x80, v85
	v_mul_f32_e32 v105, v98, v104
	v_mov_b32_e32 v106, v97
	v_cvt_f32_f16_e32 v97, v92
	v_sub_f32_e32 v97, 1.0, v97
	v_mul_f32_e32 v104, v104, v97
	v_rcp_f32_e32 v107, v104
	s_nop 0
	v_mul_f32_e32 v106, v106, v107
	v_mul_f32_e32 v108, v95, v107
	ds_write2st64_b32 v81, v105, v106 offset0:10 offset1:11
	ds_write2st64_b32 v81, v108, v104 offset0:12 offset1:13
	v_mul_f32_e32 v107, v96, v104
	ds_write_b32 v85, v107 offset:3712
	s_and_saveexec_b64 s[2:3], s[10:11]
	v_cvt_f32_f16_e32 v97, v93
	ds_write_b32 v85, v97 offset:3968
	s_or_b64 exec, exec, s[2:3]
	s_and_b64 vcc, exec, s[14:15]
	s_and_b32 s2, s55, 3
	s_cmp_lg_u32 s2, 2
	s_cbranch_scc1 .LBB0_1814
	v_mul_f32_e32 v95, v95, v96
	v_mul_f32_e32 v96, v11, v95
	s_nop 1
	v_mov_b32_dpp v96, v96 quad_perm:[1,0,3,2] row_mask:0xf bank_mask:0xf bound_ctrl:1
	v_fmac_f32_e32 v96, v11, v95
	s_nop 1
	v_add_f32_dpp v95, v96, v96 quad_perm:[2,3,0,1] row_mask:0xf bank_mask:0xf bound_ctrl:1
	s_nop 1
	v_add_f32_dpp v95, v95, v95 row_half_mirror row_mask:0xf bank_mask:0xf bound_ctrl:1
	s_nop 1
	v_add_f32_dpp v95, v95, v95 row_mirror row_mask:0xf bank_mask:0xf bound_ctrl:1
	v_mov_b32_e32 v96, v95
	s_nop 1
	v_permlane16_swap_b32 v96, v95
	s_nop 1
	s_nop 0
	v_add_f32_e32 v95, v96, v95
	v_mov_b32_e32 v96, v95
	s_nop 1
	v_permlane32_swap_b32 v96, v95
	s_nop 1
	s_and_saveexec_b64 s[2:3], s[12:13]
	s_cbranch_execz .LBB0_1813
	s_or_b32 s17, s82, 2
	s_add_i32 s16, s67, 2
	s_cmpk_lt_i32 s16, 0x100
	s_mov_b64 s[58:59], -1
	s_cbranch_scc1 .LBB0_1807
	s_andn2_b64 vcc, exec, s[0:1]
	s_cbranch_vccnz .LBB0_1804
	s_sub_i32 s16, s44, s17
	s_mov_b64 s[58:59], 0

.LBB0_1814:
	v_cvt_f32_f16_sdwa v91, v91 dst_sel:DWORD dst_unused:UNUSED_PAD src0_sel:WORD_1
	v_cvt_f32_f16_sdwa v94, v94 dst_sel:DWORD dst_unused:UNUSED_PAD src0_sel:WORD_1
	v_cvt_f32_f16_sdwa v92, v92 dst_sel:DWORD dst_unused:UNUSED_PAD src0_sel:WORD_1
	v_mul_f32_e32 v80, v10, v80
	v_cvt_f32_f16_sdwa v90, v90 dst_sel:DWORD dst_unused:UNUSED_PAD src0_sel:WORD_1
	v_mul_f32_e32 v95, v80, v91
	v_add_f32_e32 v80, -1.0, v94
	v_fma_f32 v80, v12, v80, 1.0
	v_mul_f32_e32 v91, v80, v91
	v_mul_f32_e64 v94, v95, -v94
	v_add_u32_e32 v80, 0xc0, v85
	v_sub_f32_e32 v92, 1.0, v92
	v_mul_f32_e32 v105, v95, v104
	v_mov_b32_e32 v106, v94
	v_mul_f32_e32 v104, v104, v92
	v_rcp_f32_e32 v107, v104
	s_nop 0
	v_mul_f32_e32 v106, v106, v107
	v_mul_f32_e32 v108, v91, v107
	ds_write2st64_b32 v80, v105, v106 offset0:15 offset1:16
	ds_write2st64_b32 v80, v108, v104 offset0:17 offset1:18
	v_mul_f32_e32 v107, v90, v104
	ds_write_b32 v85, v107 offset:5056
	s_and_saveexec_b64 s[2:3], s[10:11]
	v_cvt_f32_f16_sdwa v92, v93 dst_sel:DWORD dst_unused:UNUSED_PAD src0_sel:WORD_1
	ds_write_b32 v85, v92 offset:5312
	s_or_b64 exec, exec, s[2:3]
	s_and_b64 vcc, exec, s[14:15]
	s_and_b32 s2, s55, 3
	s_cmp_lg_u32 s2, 3
	s_cbranch_scc1 .LBB0_1831
	v_mul_f32_e32 v90, v91, v90
	v_mul_f32_e32 v91, v11, v90
	s_nop 1
	v_mov_b32_dpp v91, v91 quad_perm:[1,0,3,2] row_mask:0xf bank_mask:0xf bound_ctrl:1
	v_fmac_f32_e32 v91, v11, v90
	s_nop 1
	v_add_f32_dpp v90, v91, v91 quad_perm:[2,3,0,1] row_mask:0xf bank_mask:0xf bound_ctrl:1
	s_nop 1
	v_add_f32_dpp v90, v90, v90 row_half_mirror row_mask:0xf bank_mask:0xf bound_ctrl:1
	s_nop 1
	v_add_f32_dpp v90, v90, v90 row_mirror row_mask:0xf bank_mask:0xf bound_ctrl:1
	v_mov_b32_e32 v91, v90
	s_nop 1
	v_permlane16_swap_b32 v90, v91
	s_nop 1
	s_nop 0
	v_add_f32_e32 v90, v90, v91
	v_mov_b32_e32 v91, v90
	s_nop 1
	v_permlane32_swap_b32 v90, v91
	s_nop 1
	s_and_saveexec_b64 s[2:3], s[12:13]
	s_cbranch_execz .LBB0_1830
	s_or_b32 s17, s82, 3
	s_add_i32 s16, s67, 3
	s_cmpk_lt_i32 s16, 0x100
	s_mov_b64 s[58:59], -1
	s_cbranch_scc1 .LBB0_1824
	s_andn2_b64 vcc, exec, s[0:1]
	s_cbranch_vccnz .LBB0_1821
	s_sub_i32 s16, s44, s17
	s_mov_b64 s[58:59], 0

.LBB0_1831:
	v_cvt_f32_f16_e32 v90, v86
	v_cvt_f32_f16_e32 v91, v89
	v_mul_f32_e32 v76, v10, v76
	v_mul_f32_e32 v92, v76, v90
	v_add_f32_e32 v76, -1.0, v91
	v_mul_f32_e64 v91, v92, -v91
	v_fma_f32 v76, v12, v76, 1.0
	v_mul_f32_e32 v105, v92, v104
	v_mov_b32_e32 v106, v91
	v_cvt_f32_f16_e32 v91, v87
	v_mul_f32_e32 v76, v76, v90
	v_cvt_f32_f16_e32 v90, v83
	v_sub_f32_e32 v91, 1.0, v91
	v_mul_f32_e32 v104, v104, v91
	v_rcp_f32_e32 v107, v104
	s_nop 0
	v_mul_f32_e32 v106, v106, v107
	v_mul_f32_e32 v108, v76, v107
	ds_write2st64_b32 v85, v105, v106 offset0:21 offset1:22
	ds_write2st64_b32 v85, v108, v104 offset0:23 offset1:24
	v_mul_f32_e32 v107, v90, v104
	ds_write_b32 v85, v107 offset:6400
	s_and_saveexec_b64 s[2:3], s[10:11]
	v_cvt_f32_f16_e32 v91, v88
	ds_write_b32 v85, v91 offset:6656
	s_or_b64 exec, exec, s[2:3]
	s_and_b64 vcc, exec, s[14:15]
	s_and_b32 s2, s55, 3
	s_cmp_lg_u32 s2, 0
	s_cbranch_scc1 .LBB0_1848
	v_mul_f32_e32 v76, v76, v90
	v_mul_f32_e32 v90, v11, v76
	s_nop 1
	v_mov_b32_dpp v90, v90 quad_perm:[1,0,3,2] row_mask:0xf bank_mask:0xf bound_ctrl:1
	v_fmac_f32_e32 v90, v11, v76
	s_nop 1
	v_add_f32_dpp v76, v90, v90 quad_perm:[2,3,0,1] row_mask:0xf bank_mask:0xf bound_ctrl:1
	s_nop 1
	v_add_f32_dpp v76, v76, v76 row_half_mirror row_mask:0xf bank_mask:0xf bound_ctrl:1
	s_nop 1
	v_add_f32_dpp v76, v76, v76 row_mirror row_mask:0xf bank_mask:0xf bound_ctrl:1
	v_mov_b32_e32 v90, v76
	s_nop 1
	v_permlane16_swap_b32 v76, v90
	s_nop 1
	s_nop 0
	v_add_f32_e32 v76, v76, v90
	v_mov_b32_e32 v90, v76
	s_nop 1
	v_permlane32_swap_b32 v76, v90
	s_nop 1
	s_and_saveexec_b64 s[2:3], s[12:13]
	s_cbranch_execz .LBB0_1847
	s_or_b32 s17, s82, 4
	s_add_i32 s16, s67, 4
	s_cmpk_lt_i32 s16, 0x100
	s_mov_b64 s[58:59], -1
	s_cbranch_scc1 .LBB0_1841
	s_andn2_b64 vcc, exec, s[0:1]
	s_cbranch_vccnz .LBB0_1838
	s_sub_i32 s16, s44, s17
	s_mov_b64 s[58:59], 0

.LBB0_1848:
	v_cvt_f32_f16_sdwa v76, v86 dst_sel:DWORD dst_unused:UNUSED_PAD src0_sel:WORD_1
	v_cvt_f32_f16_sdwa v86, v89 dst_sel:DWORD dst_unused:UNUSED_PAD src0_sel:WORD_1
	v_mul_f32_e32 v57, v10, v57
	v_cvt_f32_f16_sdwa v87, v87 dst_sel:DWORD dst_unused:UNUSED_PAD src0_sel:WORD_1
	v_mul_f32_e32 v89, v57, v76
	v_add_f32_e32 v57, -1.0, v86
	v_fma_f32 v57, v12, v57, 1.0
	v_mul_f32_e32 v57, v57, v76
	v_cvt_f32_f16_sdwa v76, v83 dst_sel:DWORD dst_unused:UNUSED_PAD src0_sel:WORD_1
	v_mul_f32_e64 v83, v89, -v86
	v_mul_f32_e32 v105, v89, v104
	v_mov_b32_e32 v106, v83
	v_sub_f32_e32 v83, 1.0, v87
	v_mul_f32_e32 v104, v104, v83
	v_rcp_f32_e32 v107, v104
	s_nop 0
	v_mul_f32_e32 v106, v106, v107
	v_mul_f32_e32 v108, v57, v107
	ds_write2st64_b32 v82, v105, v106 offset0:26 offset1:27
	ds_write2st64_b32 v82, v108, v104 offset0:28 offset1:29
	v_mul_f32_e32 v107, v76, v104
	ds_write_b32 v85, v107 offset:7744
	s_and_saveexec_b64 s[2:3], s[10:11]
	v_cvt_f32_f16_sdwa v82, v88 dst_sel:DWORD dst_unused:UNUSED_PAD src0_sel:WORD_1
	ds_write_b32 v85, v82 offset:8000
	s_or_b64 exec, exec, s[2:3]
	s_and_b64 vcc, exec, s[14:15]
	s_and_b32 s2, s55, 3
	s_cmp_lg_u32 s2, 1
	s_cbranch_scc1 .LBB0_1865
	v_mul_f32_e32 v57, v57, v76
	v_mul_f32_e32 v76, v11, v57
	s_nop 1
	v_mov_b32_dpp v76, v76 quad_perm:[1,0,3,2] row_mask:0xf bank_mask:0xf bound_ctrl:1
	v_fmac_f32_e32 v76, v11, v57
	s_nop 1
	v_add_f32_dpp v57, v76, v76 quad_perm:[2,3,0,1] row_mask:0xf bank_mask:0xf bound_ctrl:1
	s_nop 1
	v_add_f32_dpp v57, v57, v57 row_half_mirror row_mask:0xf bank_mask:0xf bound_ctrl:1
	s_nop 1
	v_add_f32_dpp v57, v57, v57 row_mirror row_mask:0xf bank_mask:0xf bound_ctrl:1
	v_mov_b32_e32 v76, v57
	s_nop 1
	v_permlane16_swap_b32 v57, v76
	s_nop 1
	s_nop 0
	v_add_f32_e32 v57, v57, v76
	v_mov_b32_e32 v76, v57
	s_nop 1
	v_permlane32_swap_b32 v57, v76
	s_nop 1
	s_and_saveexec_b64 s[2:3], s[12:13]
	s_cbranch_execz .LBB0_1864
	s_or_b32 s17, s82, 5
	s_add_i32 s16, s67, 5
	s_cmpk_lt_i32 s16, 0x100
	s_mov_b64 s[58:59], -1
	s_cbranch_scc1 .LBB0_1858
	s_andn2_b64 vcc, exec, s[0:1]
	s_cbranch_vccnz .LBB0_1855
	s_sub_i32 s16, s44, s17
	s_mov_b64 s[58:59], 0

.LBB0_1865:
	v_cvt_f32_f16_e32 v57, v30
	v_cvt_f32_f16_e32 v76, v37
	v_mul_f32_e32 v47, v10, v47
	v_mul_f32_e32 v82, v47, v57
	v_add_f32_e32 v47, -1.0, v76
	v_mul_f32_e64 v76, v82, -v76
	v_fma_f32 v47, v12, v47, 1.0
	v_mul_f32_e32 v105, v82, v104
	v_mov_b32_e32 v106, v76
	v_cvt_f32_f16_e32 v76, v32
	v_mul_f32_e32 v47, v47, v57
	v_cvt_f32_f16_e32 v57, v25
	v_sub_f32_e32 v76, 1.0, v76
	v_mul_f32_e32 v104, v104, v76
	v_rcp_f32_e32 v107, v104
	s_nop 0
	v_mul_f32_e32 v106, v106, v107
	v_mul_f32_e32 v108, v47, v107
	ds_write2st64_b32 v81, v105, v106 offset0:31 offset1:32
	ds_write2st64_b32 v81, v108, v104 offset0:33 offset1:34
	v_mul_f32_e32 v107, v57, v104
	ds_write_b32 v85, v107 offset:9088
	s_and_saveexec_b64 s[2:3], s[10:11]
	v_cvt_f32_f16_e32 v76, v34
	ds_write_b32 v85, v76 offset:9344
	s_or_b64 exec, exec, s[2:3]
	s_and_b64 vcc, exec, s[14:15]
	s_and_b32 s2, s55, 3
	s_cmp_lg_u32 s2, 2
	s_cbranch_scc1 .LBB0_1882
	v_mul_f32_e32 v47, v47, v57
	v_mul_f32_e32 v57, v11, v47
	s_nop 1
	v_mov_b32_dpp v57, v57 quad_perm:[1,0,3,2] row_mask:0xf bank_mask:0xf bound_ctrl:1
	v_fmac_f32_e32 v57, v11, v47
	s_nop 1
	v_add_f32_dpp v47, v57, v57 quad_perm:[2,3,0,1] row_mask:0xf bank_mask:0xf bound_ctrl:1
	s_nop 1
	v_add_f32_dpp v47, v47, v47 row_half_mirror row_mask:0xf bank_mask:0xf bound_ctrl:1
	s_nop 1
	v_add_f32_dpp v47, v47, v47 row_mirror row_mask:0xf bank_mask:0xf bound_ctrl:1
	v_mov_b32_e32 v57, v47
	s_nop 1
	v_permlane16_swap_b32 v47, v57
	s_nop 1
	s_nop 0
	v_add_f32_e32 v47, v47, v57
	v_mov_b32_e32 v57, v47
	s_nop 1
	v_permlane32_swap_b32 v47, v57
	s_nop 1
	s_and_saveexec_b64 s[2:3], s[12:13]
	s_cbranch_execz .LBB0_1881
	s_or_b32 s17, s82, 6
	s_add_i32 s16, s67, 6
	s_cmpk_lt_i32 s16, 0x100
	s_mov_b64 s[58:59], -1
	s_cbranch_scc1 .LBB0_1875
	s_andn2_b64 vcc, exec, s[0:1]
	s_cbranch_vccnz .LBB0_1872
	s_sub_i32 s16, s44, s17
	s_mov_b64 s[58:59], 0

.LBB0_1882:
	v_cvt_f32_f16_sdwa v37, v37 dst_sel:DWORD dst_unused:UNUSED_PAD src0_sel:WORD_1
	v_cvt_f32_f16_sdwa v30, v30 dst_sel:DWORD dst_unused:UNUSED_PAD src0_sel:WORD_1
	v_cvt_f32_f16_sdwa v32, v32 dst_sel:DWORD dst_unused:UNUSED_PAD src0_sel:WORD_1
	v_cvt_f32_f16_sdwa v25, v25 dst_sel:DWORD dst_unused:UNUSED_PAD src0_sel:WORD_1
	s_waitcnt vmcnt(48)
	v_mul_f32_e32 v35, v10, v35
	v_add_f32_e32 v47, -1.0, v37
	v_mul_f32_e32 v35, v35, v30
	v_fma_f32 v47, v12, v47, 1.0
	v_mul_f32_e32 v30, v47, v30
	v_mul_f32_e64 v37, v35, -v37
	v_sub_f32_e32 v32, 1.0, v32
	v_mul_f32_e32 v105, v35, v104
	v_mov_b32_e32 v106, v37
	v_mul_f32_e32 v104, v104, v32
	v_rcp_f32_e32 v107, v104
	s_nop 0
	v_mul_f32_e32 v106, v106, v107
	v_mul_f32_e32 v108, v30, v107
	ds_write2st64_b32 v80, v105, v106 offset0:36 offset1:37
	ds_write2st64_b32 v80, v108, v104 offset0:38 offset1:39
	v_mul_f32_e32 v107, v25, v104
	ds_write_b32 v85, v107 offset:10432
	s_and_saveexec_b64 s[2:3], s[10:11]
	v_cvt_f32_f16_sdwa v32, v34 dst_sel:DWORD dst_unused:UNUSED_PAD src0_sel:WORD_1
	ds_write_b32 v85, v32 offset:10688
	s_or_b64 exec, exec, s[2:3]
	s_and_b64 vcc, exec, s[14:15]
	s_and_b32 s2, s55, 3
	s_cmp_lg_u32 s2, 3
	s_cbranch_scc1 .LBB0_1899
	v_mul_f32_e32 v25, v30, v25
	v_mul_f32_e32 v30, v11, v25
	s_nop 1
	v_mov_b32_dpp v30, v30 quad_perm:[1,0,3,2] row_mask:0xf bank_mask:0xf bound_ctrl:1
	v_fmac_f32_e32 v30, v11, v25
	s_nop 1
	v_add_f32_dpp v25, v30, v30 quad_perm:[2,3,0,1] row_mask:0xf bank_mask:0xf bound_ctrl:1
	s_nop 1
	v_add_f32_dpp v25, v25, v25 row_half_mirror row_mask:0xf bank_mask:0xf bound_ctrl:1
	s_nop 1
	v_add_f32_dpp v25, v25, v25 row_mirror row_mask:0xf bank_mask:0xf bound_ctrl:1
	v_mov_b32_e32 v30, v25
	s_nop 1
	v_permlane16_swap_b32 v30, v25
	s_nop 1
	s_nop 0
	v_add_f32_e32 v25, v30, v25
	v_mov_b32_e32 v30, v25
	s_nop 1
	v_permlane32_swap_b32 v30, v25
	s_nop 1
	s_and_saveexec_b64 s[2:3], s[12:13]
	s_cbranch_execz .LBB0_1898
	s_or_b32 s17, s82, 7
	s_add_i32 s67, s67, 7
	s_cmpk_lt_i32 s67, 0x100
	s_mov_b64 s[58:59], -1
	s_cbranch_scc1 .LBB0_1892
	s_andn2_b64 vcc, exec, s[0:1]
	s_cbranch_vccnz .LBB0_1889
	s_sub_i32 s16, s44, s17
	s_mov_b64 s[58:59], 0

.LBB0_1901:
	v_cvt_f32_f16_e32 v0, v55
	v_cvt_f32_f16_e32 v3, v67
	v_mul_f32_e32 v1, v10, v53
	v_cvt_f32_f16_e32 v5, v52
	v_mul_f32_e32 v4, v1, v0
	v_add_f32_e32 v1, -1.0, v3
	v_cvt_f32_f16_e32 v2, v49
	v_fma_f32 v1, v12, v1, 1.0
	s_mul_i32 s2, s81, 0x2a00
	v_mul_f32_e32 v1, v1, v0
	v_add_u32_e32 v0, s2, v84
	v_mul_f32_e64 v3, v4, -v3
	v_mov_b32_e32 v104, 1.0
	v_mul_f32_e32 v105, v4, v104
	v_mov_b32_e32 v106, v3
	v_sub_f32_e32 v3, 1.0, v5
	v_mul_f32_e32 v104, v104, v3
	v_rcp_f32_e32 v107, v104
	s_nop 0
	v_mul_f32_e32 v106, v106, v107
	v_mul_f32_e32 v108, v1, v107
	ds_write2st64_b32 v0, v105, v106 offset1:1
	ds_write2st64_b32 v0, v108, v104 offset0:2 offset1:3
	v_mul_f32_e32 v107, v2, v104
	ds_write_b32 v0, v107 offset:1024
	s_and_saveexec_b64 s[2:3], s[10:11]
	v_cvt_f32_f16_e32 v3, v51
	ds_write_b32 v0, v3 offset:1280
	s_or_b64 exec, exec, s[2:3]
	s_and_b64 vcc, exec, s[14:15]
	s_cbranch_vccnz .LBB0_1907
	v_mul_f32_e32 v1, v1, v2
	v_mul_f32_e32 v2, v11, v1
	s_nop 1
	v_mov_b32_dpp v2, v2 quad_perm:[1,0,3,2] row_mask:0xf bank_mask:0xf bound_ctrl:1
	v_fmac_f32_e32 v2, v11, v1
	s_nop 1
	v_add_f32_dpp v1, v2, v2 quad_perm:[2,3,0,1] row_mask:0xf bank_mask:0xf bound_ctrl:1
	s_nop 1
	v_add_f32_dpp v1, v1, v1 row_half_mirror row_mask:0xf bank_mask:0xf bound_ctrl:1
	s_nop 1
	v_add_f32_dpp v1, v1, v1 row_mirror row_mask:0xf bank_mask:0xf bound_ctrl:1
	v_mov_b32_e32 v2, v1
	s_nop 1
	v_permlane16_swap_b32 v1, v2
	s_nop 1
	s_nop 0
	v_add_f32_e32 v1, v1, v2
	v_mov_b32_e32 v2, v1
	s_nop 1
	v_permlane32_swap_b32 v1, v2
	s_nop 1
	s_and_saveexec_b64 s[2:3], s[12:13]
	s_cbranch_execz .LBB0_1906
	v_readlane_b32 s16, v254, 47
	s_sub_i32 s33, s44, s16
	s_add_i32 s58, s16, s62
	s_and_b64 s[16:17], s[56:57], exec
	s_cselect_b32 s16, s58, s33
	s_ashr_i32 s17, s16, 31
	s_lshl_b64 s[16:17], s[16:17], 6
	s_add_u32 s16, s76, s16
	v_add_f32_e32 v1, v1, v2
	s_addc_u32 s17, s64, s17
	global_store_dword v153, v1, s[16:17]

.LBB0_1907:
	v_cvt_f32_f16_e32 v1, v74
	v_cvt_f32_f16_e32 v4, v78
	v_mul_f32_e32 v2, v10, v73
	v_cvt_f32_f16_e32 v6, v72
	v_mul_f32_e32 v5, v2, v1
	v_add_f32_e32 v2, -1.0, v4
	v_cvt_f32_f16_e32 v3, v70
	v_fma_f32 v2, v12, v2, 1.0
	v_mul_f32_e32 v2, v2, v1
	v_mul_f32_e64 v4, v5, -v4
	v_add_u32_e32 v1, 64, v0
	v_mul_f32_e32 v105, v5, v104
	v_mov_b32_e32 v106, v4
	v_sub_f32_e32 v4, 1.0, v6
	v_mul_f32_e32 v104, v104, v4
	v_rcp_f32_e32 v107, v104
	s_nop 0
	v_mul_f32_e32 v106, v106, v107
	v_mul_f32_e32 v108, v2, v107
	ds_write2st64_b32 v1, v105, v106 offset0:5 offset1:6
	ds_write2st64_b32 v1, v108, v104 offset0:7 offset1:8
	v_mul_f32_e32 v107, v3, v104
	ds_write_b32 v0, v107 offset:2368
	s_and_saveexec_b64 s[2:3], s[10:11]
	v_cvt_f32_f16_e32 v4, v71
	ds_write_b32 v0, v4 offset:2624
	s_or_b64 exec, exec, s[2:3]
	s_and_b64 vcc, exec, s[14:15]
	s_cbranch_vccnz .LBB0_1924
	v_mul_f32_e32 v2, v2, v3
	v_mul_f32_e32 v3, v11, v2
	s_nop 1
	v_mov_b32_dpp v3, v3 quad_perm:[1,0,3,2] row_mask:0xf bank_mask:0xf bound_ctrl:1
	v_fmac_f32_e32 v3, v11, v2
	s_nop 1
	v_add_f32_dpp v2, v3, v3 quad_perm:[2,3,0,1] row_mask:0xf bank_mask:0xf bound_ctrl:1
	s_nop 1
	v_add_f32_dpp v2, v2, v2 row_half_mirror row_mask:0xf bank_mask:0xf bound_ctrl:1
	s_nop 1
	v_add_f32_dpp v2, v2, v2 row_mirror row_mask:0xf bank_mask:0xf bound_ctrl:1
	v_mov_b32_e32 v3, v2
	s_nop 1
	v_permlane16_swap_b32 v2, v3
	s_nop 1
	s_nop 0
	v_add_f32_e32 v2, v2, v3
	v_mov_b32_e32 v3, v2
	s_nop 1
	v_permlane32_swap_b32 v2, v3
	s_nop 1
	s_and_saveexec_b64 s[2:3], s[12:13]
	s_cbranch_execz .LBB0_1923
	v_readlane_b32 s16, v254, 49
	v_readlane_b32 s17, v254, 50
	s_andn2_b64 vcc, exec, s[16:17]
	s_mov_b64 s[56:57], -1
	s_cbranch_vccnz .LBB0_1917
	s_andn2_b64 vcc, exec, s[0:1]
	s_cbranch_vccnz .LBB0_1914
	v_readlane_b32 s16, v254, 48
	s_sub_i32 s16, s44, s16
	s_mov_b64 s[56:57], 0

.LBB0_1924:
	v_cvt_f32_f16_e32 v2, v68
	v_cvt_f32_f16_e32 v5, v69
	v_mul_f32_e32 v3, v10, v58
	v_cvt_f32_f16_e32 v7, v59
	v_mul_f32_e32 v6, v3, v2
	v_add_f32_e32 v3, -1.0, v5
	v_cvt_f32_f16_e32 v4, v54
	v_fma_f32 v3, v12, v3, 1.0
	v_mul_f32_e32 v3, v3, v2
	v_mul_f32_e64 v5, v6, -v5
	v_add_u32_e32 v2, 0x80, v0
	v_mul_f32_e32 v105, v6, v104
	v_mov_b32_e32 v106, v5
	v_sub_f32_e32 v5, 1.0, v7
	v_mul_f32_e32 v104, v104, v5
	v_rcp_f32_e32 v107, v104
	s_nop 0
	v_mul_f32_e32 v106, v106, v107
	v_mul_f32_e32 v108, v3, v107
	ds_write2st64_b32 v2, v105, v106 offset0:10 offset1:11
	ds_write2st64_b32 v2, v108, v104 offset0:12 offset1:13
	v_mul_f32_e32 v107, v4, v104
	ds_write_b32 v0, v107 offset:3712
	s_and_saveexec_b64 s[2:3], s[10:11]
	v_cvt_f32_f16_e32 v5, v56
	ds_write_b32 v0, v5 offset:3968
	s_or_b64 exec, exec, s[2:3]
	s_and_b64 vcc, exec, s[14:15]
	s_cbranch_vccnz .LBB0_1941
	v_mul_f32_e32 v3, v3, v4
	v_mul_f32_e32 v4, v11, v3
	s_nop 1
	v_mov_b32_dpp v4, v4 quad_perm:[1,0,3,2] row_mask:0xf bank_mask:0xf bound_ctrl:1
	v_fmac_f32_e32 v4, v11, v3
	s_nop 1
	v_add_f32_dpp v3, v4, v4 quad_perm:[2,3,0,1] row_mask:0xf bank_mask:0xf bound_ctrl:1
	s_nop 1
	v_add_f32_dpp v3, v3, v3 row_half_mirror row_mask:0xf bank_mask:0xf bound_ctrl:1
	s_nop 1
	v_add_f32_dpp v3, v3, v3 row_mirror row_mask:0xf bank_mask:0xf bound_ctrl:1
	v_mov_b32_e32 v4, v3
	s_nop 1
	v_permlane16_swap_b32 v3, v4
	s_nop 1
	s_nop 0
	v_add_f32_e32 v3, v3, v4
	v_mov_b32_e32 v4, v3
	s_nop 1
	v_permlane32_swap_b32 v3, v4
	s_nop 1
	s_and_saveexec_b64 s[2:3], s[12:13]
	s_cbranch_execz .LBB0_1940
	v_readlane_b32 s16, v254, 52
	v_readlane_b32 s17, v254, 53
	s_andn2_b64 vcc, exec, s[16:17]
	s_mov_b64 s[56:57], -1
	s_cbranch_vccnz .LBB0_1934
	s_andn2_b64 vcc, exec, s[0:1]
	s_cbranch_vccnz .LBB0_1931
	v_readlane_b32 s16, v254, 51
	s_sub_i32 s16, s44, s16
	s_mov_b64 s[56:57], 0

.LBB0_1941:
	v_cvt_f32_f16_e32 v3, v48
	v_cvt_f32_f16_e32 v6, v50
	v_mul_f32_e32 v4, v10, v45
	v_cvt_f32_f16_e32 v8, v46
	v_mul_f32_e32 v7, v4, v3
	v_add_f32_e32 v4, -1.0, v6
	v_cvt_f32_f16_e32 v5, v43
	v_fma_f32 v4, v12, v4, 1.0
	v_mul_f32_e32 v4, v4, v3
	v_mul_f32_e64 v6, v7, -v6
	v_add_u32_e32 v3, 0xc0, v0
	v_mul_f32_e32 v105, v7, v104
	v_mov_b32_e32 v106, v6
	v_sub_f32_e32 v6, 1.0, v8
	v_mul_f32_e32 v104, v104, v6
	v_rcp_f32_e32 v107, v104
	s_nop 0
	v_mul_f32_e32 v106, v106, v107
	v_mul_f32_e32 v108, v4, v107
	ds_write2st64_b32 v3, v105, v106 offset0:15 offset1:16
	ds_write2st64_b32 v3, v108, v104 offset0:17 offset1:18
	v_mul_f32_e32 v107, v5, v104
	ds_write_b32 v0, v107 offset:5056
	s_and_saveexec_b64 s[2:3], s[10:11]
	v_cvt_f32_f16_e32 v6, v44
	ds_write_b32 v0, v6 offset:5312
	s_or_b64 exec, exec, s[2:3]
	s_and_b64 vcc, exec, s[14:15]
	s_cbranch_vccnz .LBB0_1958
	v_mul_f32_e32 v4, v4, v5
	v_mul_f32_e32 v5, v11, v4
	s_nop 1
	v_mov_b32_dpp v5, v5 quad_perm:[1,0,3,2] row_mask:0xf bank_mask:0xf bound_ctrl:1
	v_fmac_f32_e32 v5, v11, v4
	s_nop 1
	v_add_f32_dpp v4, v5, v5 quad_perm:[2,3,0,1] row_mask:0xf bank_mask:0xf bound_ctrl:1
	s_nop 1
	v_add_f32_dpp v4, v4, v4 row_half_mirror row_mask:0xf bank_mask:0xf bound_ctrl:1
	s_nop 1
	v_add_f32_dpp v4, v4, v4 row_mirror row_mask:0xf bank_mask:0xf bound_ctrl:1
	v_mov_b32_e32 v5, v4
	s_nop 1
	v_permlane16_swap_b32 v5, v4
	s_nop 1
	s_nop 0
	v_add_f32_e32 v4, v5, v4
	v_mov_b32_e32 v5, v4
	s_nop 1
	v_permlane32_swap_b32 v5, v4
	s_nop 1
	s_and_saveexec_b64 s[2:3], s[12:13]
	s_cbranch_execz .LBB0_1957
	v_readlane_b32 s16, v254, 55
	v_readlane_b32 s17, v254, 56
	s_andn2_b64 vcc, exec, s[16:17]
	s_mov_b64 s[56:57], -1
	s_cbranch_vccnz .LBB0_1951
	s_andn2_b64 vcc, exec, s[0:1]
	s_cbranch_vccnz .LBB0_1948
	v_readlane_b32 s16, v254, 54
	s_sub_i32 s16, s44, s16
	s_mov_b64 s[56:57], 0

.LBB0_1958:
	v_cvt_f32_f16_e32 v4, v41
	v_cvt_f32_f16_e32 v6, v42
	v_mul_f32_e32 v5, v10, v38
	v_cvt_f32_f16_e32 v8, v40
	v_mul_f32_e32 v7, v5, v4
	v_add_f32_e32 v5, -1.0, v6
	v_fma_f32 v5, v12, v5, 1.0
	v_mul_f32_e32 v4, v5, v4
	v_cvt_f32_f16_e32 v5, v36
	v_mul_f32_e64 v6, v7, -v6
	v_mul_f32_e32 v105, v7, v104
	v_mov_b32_e32 v106, v6
	v_sub_f32_e32 v6, 1.0, v8
	v_mul_f32_e32 v104, v104, v6
	v_rcp_f32_e32 v107, v104
	s_nop 0
	v_mul_f32_e32 v106, v106, v107
	v_mul_f32_e32 v108, v4, v107
	ds_write2st64_b32 v0, v105, v106 offset0:21 offset1:22
	ds_write2st64_b32 v0, v108, v104 offset0:23 offset1:24
	v_mul_f32_e32 v107, v5, v104
	ds_write_b32 v0, v107 offset:6400
	s_and_saveexec_b64 s[2:3], s[10:11]
	v_cvt_f32_f16_e32 v6, v39
	ds_write_b32 v0, v6 offset:6656
	s_or_b64 exec, exec, s[2:3]
	s_and_b64 vcc, exec, s[14:15]
	s_cbranch_vccnz .LBB0_1975
	v_mul_f32_e32 v4, v4, v5
	v_mul_f32_e32 v5, v11, v4
	s_nop 1
	v_mov_b32_dpp v5, v5 quad_perm:[1,0,3,2] row_mask:0xf bank_mask:0xf bound_ctrl:1
	v_fmac_f32_e32 v5, v11, v4
	s_nop 1
	v_add_f32_dpp v4, v5, v5 quad_perm:[2,3,0,1] row_mask:0xf bank_mask:0xf bound_ctrl:1
	s_nop 1
	v_add_f32_dpp v4, v4, v4 row_half_mirror row_mask:0xf bank_mask:0xf bound_ctrl:1
	s_nop 1
	v_add_f32_dpp v4, v4, v4 row_mirror row_mask:0xf bank_mask:0xf bound_ctrl:1
	v_mov_b32_e32 v5, v4
	s_nop 1
	v_permlane16_swap_b32 v4, v5
	s_nop 1
	s_nop 0
	v_add_f32_e32 v4, v4, v5
	v_mov_b32_e32 v5, v4
	s_nop 1
	v_permlane32_swap_b32 v4, v5
	s_nop 1
	s_and_saveexec_b64 s[2:3], s[12:13]
	s_cbranch_execz .LBB0_1974
	v_readlane_b32 s16, v254, 58
	v_readlane_b32 s17, v254, 59
	s_andn2_b64 vcc, exec, s[16:17]
	s_mov_b64 s[56:57], -1
	s_cbranch_vccnz .LBB0_1968
	s_andn2_b64 vcc, exec, s[0:1]
	s_cbranch_vccnz .LBB0_1965
	v_readlane_b32 s16, v254, 57
	s_sub_i32 s16, s44, s16
	s_mov_b64 s[56:57], 0

.LBB0_1975:
	v_cvt_f32_f16_e32 v4, v31
	v_cvt_f32_f16_e32 v6, v33
	v_mul_f32_e32 v5, v10, v27
	v_cvt_f32_f16_e32 v8, v29
	v_mul_f32_e32 v7, v5, v4
	v_add_f32_e32 v5, -1.0, v6
	v_fma_f32 v5, v12, v5, 1.0
	v_mul_f32_e32 v4, v5, v4
	v_cvt_f32_f16_e32 v5, v26
	v_mul_f32_e64 v6, v7, -v6
	v_mul_f32_e32 v105, v7, v104
	v_mov_b32_e32 v106, v6
	v_sub_f32_e32 v6, 1.0, v8
	v_mul_f32_e32 v104, v104, v6
	v_rcp_f32_e32 v107, v104
	s_nop 0
	v_mul_f32_e32 v106, v106, v107
	v_mul_f32_e32 v108, v4, v107
	ds_write2st64_b32 v1, v105, v106 offset0:26 offset1:27
	ds_write2st64_b32 v1, v108, v104 offset0:28 offset1:29
	v_mul_f32_e32 v107, v5, v104
	ds_write_b32 v0, v107 offset:7744
	s_and_saveexec_b64 s[2:3], s[10:11]
	v_cvt_f32_f16_e32 v1, v28
	ds_write_b32 v0, v1 offset:8000
	s_or_b64 exec, exec, s[2:3]
	s_and_b64 vcc, exec, s[14:15]
	s_cbranch_vccnz .LBB0_1992
	v_mul_f32_e32 v1, v4, v5
	v_mul_f32_e32 v4, v11, v1
	s_nop 1
	v_mov_b32_dpp v4, v4 quad_perm:[1,0,3,2] row_mask:0xf bank_mask:0xf bound_ctrl:1
	v_fmac_f32_e32 v4, v11, v1
	s_nop 1
	v_add_f32_dpp v1, v4, v4 quad_perm:[2,3,0,1] row_mask:0xf bank_mask:0xf bound_ctrl:1
	s_nop 1
	v_add_f32_dpp v1, v1, v1 row_half_mirror row_mask:0xf bank_mask:0xf bound_ctrl:1
	s_nop 1
	v_add_f32_dpp v1, v1, v1 row_mirror row_mask:0xf bank_mask:0xf bound_ctrl:1
	v_mov_b32_e32 v4, v1
	s_nop 1
	v_permlane16_swap_b32 v1, v4
	s_nop 1
	s_nop 0
	v_add_f32_e32 v1, v1, v4
	v_mov_b32_e32 v4, v1
	s_nop 1
	v_permlane32_swap_b32 v1, v4
	s_nop 1
	s_and_saveexec_b64 s[2:3], s[12:13]
	s_cbranch_execz .LBB0_1991
	v_readlane_b32 s16, v254, 61
	v_readlane_b32 s17, v254, 62
	s_andn2_b64 vcc, exec, s[16:17]
	s_mov_b64 s[56:57], -1
	s_cbranch_vccnz .LBB0_1985
	s_andn2_b64 vcc, exec, s[0:1]
	s_cbranch_vccnz .LBB0_1982
	v_readlane_b32 s16, v254, 60
	s_sub_i32 s16, s44, s16
	s_mov_b64 s[56:57], 0

.LBB0_1992:
	v_cvt_f32_f16_e32 v1, v23
	v_cvt_f32_f16_e32 v5, v24
	v_mul_f32_e32 v4, v10, v20
	v_cvt_f32_f16_e32 v7, v22
	v_mul_f32_e32 v6, v4, v1
	v_add_f32_e32 v4, -1.0, v5
	v_fma_f32 v4, v12, v4, 1.0
	v_mul_f32_e32 v1, v4, v1
	v_cvt_f32_f16_e32 v4, v19
	v_mul_f32_e64 v5, v6, -v5
	v_mul_f32_e32 v105, v6, v104
	v_mov_b32_e32 v106, v5
	v_sub_f32_e32 v5, 1.0, v7
	v_mul_f32_e32 v104, v104, v5
	v_rcp_f32_e32 v107, v104
	s_nop 0
	v_mul_f32_e32 v106, v106, v107
	v_mul_f32_e32 v108, v1, v107
	ds_write2st64_b32 v2, v105, v106 offset0:31 offset1:32
	ds_write2st64_b32 v2, v108, v104 offset0:33 offset1:34
	v_mul_f32_e32 v107, v4, v104
	ds_write_b32 v0, v107 offset:9088
	s_and_saveexec_b64 s[2:3], s[10:11]
	v_cvt_f32_f16_e32 v2, v21
	ds_write_b32 v0, v2 offset:9344
	s_or_b64 exec, exec, s[2:3]
	s_and_b64 vcc, exec, s[14:15]
	s_cbranch_vccnz .LBB0_2009
	v_mul_f32_e32 v1, v1, v4
	v_mul_f32_e32 v2, v11, v1
	s_nop 1
	v_mov_b32_dpp v2, v2 quad_perm:[1,0,3,2] row_mask:0xf bank_mask:0xf bound_ctrl:1
	v_fmac_f32_e32 v2, v11, v1
	s_nop 1
	v_add_f32_dpp v1, v2, v2 quad_perm:[2,3,0,1] row_mask:0xf bank_mask:0xf bound_ctrl:1
	s_nop 1
	v_add_f32_dpp v1, v1, v1 row_half_mirror row_mask:0xf bank_mask:0xf bound_ctrl:1
	s_nop 1
	v_add_f32_dpp v1, v1, v1 row_mirror row_mask:0xf bank_mask:0xf bound_ctrl:1
	v_mov_b32_e32 v2, v1
	s_nop 1
	v_permlane16_swap_b32 v1, v2
	s_nop 1
	s_nop 0
	v_add_f32_e32 v1, v1, v2
	v_mov_b32_e32 v2, v1
	s_nop 1
	v_permlane32_swap_b32 v1, v2
	s_nop 1
	s_and_saveexec_b64 s[2:3], s[12:13]
	s_cbranch_execz .LBB0_2008
	v_readlane_b32 s16, v255, 0
	v_readlane_b32 s17, v255, 1
	s_andn2_b64 vcc, exec, s[16:17]
	s_mov_b64 s[56:57], -1
	s_cbranch_vccnz .LBB0_2002
	s_andn2_b64 vcc, exec, s[0:1]
	s_cbranch_vccnz .LBB0_1999
	v_readlane_b32 s16, v254, 63
	s_sub_i32 s16, s44, s16
	s_mov_b64 s[56:57], 0

.LBB0_2009:
	v_cvt_f32_f16_e32 v1, v17
	v_cvt_f32_f16_e32 v4, v18
	s_waitcnt vmcnt(0)
	v_mul_f32_e32 v2, v10, v14
	v_cvt_f32_f16_e32 v6, v16
	v_mul_f32_e32 v5, v2, v1
	v_add_f32_e32 v2, -1.0, v4
	v_fma_f32 v2, v12, v2, 1.0
	v_mul_f32_e32 v1, v2, v1
	v_cvt_f32_f16_e32 v2, v13
	v_mul_f32_e64 v4, v5, -v4
	v_mul_f32_e32 v105, v5, v104
	v_mov_b32_e32 v106, v4
	v_sub_f32_e32 v4, 1.0, v6
	v_mul_f32_e32 v104, v104, v4
	v_rcp_f32_e32 v107, v104
	s_nop 0
	v_mul_f32_e32 v106, v106, v107
	v_mul_f32_e32 v108, v1, v107
	ds_write2st64_b32 v3, v105, v106 offset0:36 offset1:37
	ds_write2st64_b32 v3, v108, v104 offset0:38 offset1:39
	v_mul_f32_e32 v107, v2, v104
	ds_write_b32 v0, v107 offset:10432
	s_and_saveexec_b64 s[2:3], s[10:11]
	v_cvt_f32_f16_e32 v3, v15
	ds_write_b32 v0, v3 offset:10688
	s_or_b64 exec, exec, s[2:3]
	s_and_b64 vcc, exec, s[14:15]
	s_cbranch_vccnz .LBB0_1330
	v_mul_f32_e32 v0, v1, v2
	v_mul_f32_e32 v1, v11, v0
	s_nop 1
	v_mov_b32_dpp v1, v1 quad_perm:[1,0,3,2] row_mask:0xf bank_mask:0xf bound_ctrl:1
	v_fmac_f32_e32 v1, v11, v0
	s_nop 1
	v_add_f32_dpp v0, v1, v1 quad_perm:[2,3,0,1] row_mask:0xf bank_mask:0xf bound_ctrl:1
	s_nop 1
	v_add_f32_dpp v0, v0, v0 row_half_mirror row_mask:0xf bank_mask:0xf bound_ctrl:1
	s_nop 1
	v_add_f32_dpp v0, v0, v0 row_mirror row_mask:0xf bank_mask:0xf bound_ctrl:1
	v_mov_b32_e32 v1, v0
	s_nop 1
	v_permlane16_swap_b32 v1, v0
	s_nop 1
	s_nop 0
	v_add_f32_e32 v0, v1, v0
	v_mov_b32_e32 v1, v0
	s_nop 1
	v_permlane32_swap_b32 v1, v0
	s_nop 1
	s_and_saveexec_b64 s[2:3], s[12:13]
	s_cbranch_execz .LBB0_1329
	v_readlane_b32 s14, v255, 3
	v_readlane_b32 s15, v255, 4
	v_cndmask_b32_e64 v2, 0, 1, s[0:1]
	s_mov_b64 s[16:17], -1
	s_andn2_b64 vcc, exec, s[14:15]
	v_cmp_ne_u32_e64 s[0:1], 1, v2
	s_cbranch_vccnz .LBB0_2019
	s_and_b64 vcc, exec, s[0:1]
	s_cbranch_vccnz .LBB0_2016
	v_readlane_b32 s14, v255, 2
	s_sub_i32 s14, s44, s14
	s_mov_b64 s[16:17], 0
